# GEMM K-loops: pair-wise issue of line-mate K-slices (both 64B halves of each 128B line requested back-to-back, bursts on odd steps)
# speedup vs baseline: 1.0204x; 1.0109x over previous
.Lg0_E:
	s_waitcnt lgkmcnt(0)
	s_barrier
	ds_read_b128 v[246:249], v254 offset:16384
	ds_read_b128 v[250:253], v254 offset:17408
	ds_read_b128 v[148:151], v152
	ds_read_b128 v[144:147], v152 offset:1024
	v_mfma_f32_16x16x32_bf16 v[24:27], v[128:131], v[168:171], v[24:27]
	v_mfma_f32_16x16x32_bf16 v[20:23], v[132:135], v[168:171], v[20:23]
	v_mfma_f32_16x16x32_bf16 v[16:19], v[136:139], v[168:171], v[16:19]
	v_mfma_f32_16x16x32_bf16 v[12:15], v[140:143], v[168:171], v[12:15]
	v_mfma_f32_16x16x32_bf16 v[8:11], v[128:131], v[172:175], v[8:11]
	v_mfma_f32_16x16x32_bf16 v[4:7], v[132:135], v[172:175], v[4:7]
	v_mfma_f32_16x16x32_bf16 v[0:3], v[136:139], v[172:175], v[0:3]
	v_mfma_f32_16x16x32_bf16 v[36:39], v[140:143], v[172:175], v[36:39]
	ds_read_b128 v[136:139], v254 offset:18432
	ds_read_b128 v[140:143], v254 offset:19456
	ds_read_b128 v[168:171], v152 offset:2048
	ds_read_b128 v[172:175], v152 offset:3072
	s_waitcnt lgkmcnt(4)
	v_mfma_f32_16x16x32_bf16 v[124:127], v[246:249], v[148:151], v[124:127]
	v_mfma_f32_16x16x32_bf16 v[120:123], v[250:253], v[148:151], v[120:123]
	v_mfma_f32_16x16x32_bf16 v[108:111], v[246:249], v[144:147], v[108:111]
	v_mfma_f32_16x16x32_bf16 v[104:107], v[250:253], v[144:147], v[104:107]
	s_waitcnt lgkmcnt(2)
	v_mfma_f32_16x16x32_bf16 v[116:119], v[136:139], v[148:151], v[116:119]
	v_mfma_f32_16x16x32_bf16 v[112:115], v[140:143], v[148:151], v[112:115]
	v_mfma_f32_16x16x32_bf16 v[100:103], v[136:139], v[144:147], v[100:103]
	v_mfma_f32_16x16x32_bf16 v[96:99], v[140:143], v[144:147], v[96:99]
	s_waitcnt lgkmcnt(0)
	v_mfma_f32_16x16x32_bf16 v[92:95], v[246:249], v[168:171], v[92:95]
	ds_read_b128 v[144:147], v152 offset:4096
	ds_read_b128 v[148:151], v152 offset:5120
	v_mfma_f32_16x16x32_bf16 v[88:91], v[250:253], v[168:171], v[88:91]
	v_mfma_f32_16x16x32_bf16 v[84:87], v[136:139], v[168:171], v[84:87]
	v_mfma_f32_16x16x32_bf16 v[80:83], v[140:143], v[168:171], v[80:83]
	v_mfma_f32_16x16x32_bf16 v[76:79], v[246:249], v[172:175], v[76:79]
	v_mfma_f32_16x16x32_bf16 v[72:75], v[250:253], v[172:175], v[72:75]
	v_mfma_f32_16x16x32_bf16 v[68:71], v[136:139], v[172:175], v[68:71]
	v_mfma_f32_16x16x32_bf16 v[64:67], v[140:143], v[172:175], v[64:67]
	s_waitcnt lgkmcnt(0)
	v_mfma_f32_16x16x32_bf16 v[60:63], v[246:249], v[144:147], v[60:63]
	ds_read_b128 v[168:171], v152 offset:6144
	ds_read_b128 v[172:175], v152 offset:7168
	s_add_i32 s10, s36, 1
	v_mfma_f32_16x16x32_bf16 v[56:59], v[250:253], v[144:147], v[56:59]
	s_cmp_lg_u32 s10, 5
	s_cselect_b32 s36, s10, 0
	v_mfma_f32_16x16x32_bf16 v[52:55], v[136:139], v[144:147], v[52:55]
	s_add_i32 s35, s35, 1
	s_add_u32 s8, s8, 64
	v_mfma_f32_16x16x32_bf16 v[48:51], v[140:143], v[144:147], v[48:51]
	s_addc_u32 s9, s9, 0
	s_lshl_b32 s10, s36, 15
	v_mfma_f32_16x16x32_bf16 v[44:47], v[246:249], v[148:151], v[44:47]
	v_or_b32_e32 v254, s10, v165
	v_mfma_f32_16x16x32_bf16 v[40:43], v[250:253], v[148:151], v[40:43]
	v_add_u32_e32 v254, v254, v162
	v_mfma_f32_16x16x32_bf16 v[32:35], v[136:139], v[148:151], v[32:35]
	v_add_u32_e32 v152, s10, v164
	v_mfma_f32_16x16x32_bf16 v[28:31], v[140:143], v[148:151], v[28:31]
	v_add_u32_e32 v152, v152, v162
	s_cmp_lt_u32 s35, 29
	s_cbranch_scc0 .Lg0_Et
	s_waitcnt vmcnt(8)
.Lg0_Ew:
.Lg0_O:
	s_waitcnt lgkmcnt(0)
	s_barrier
	ds_read_b128 v[128:131], v254 offset:16384
	ds_read_b128 v[132:135], v254 offset:17408
	ds_read_b128 v[148:151], v152
	ds_read_b128 v[144:147], v152 offset:1024
	v_mfma_f32_16x16x32_bf16 v[24:27], v[246:249], v[168:171], v[24:27]
	v_mfma_f32_16x16x32_bf16 v[20:23], v[250:253], v[168:171], v[20:23]
	v_mfma_f32_16x16x32_bf16 v[16:19], v[136:139], v[168:171], v[16:19]
	v_mfma_f32_16x16x32_bf16 v[12:15], v[140:143], v[168:171], v[12:15]
	v_mfma_f32_16x16x32_bf16 v[8:11], v[246:249], v[172:175], v[8:11]
	v_mfma_f32_16x16x32_bf16 v[4:7], v[250:253], v[172:175], v[4:7]
	v_mfma_f32_16x16x32_bf16 v[0:3], v[136:139], v[172:175], v[0:3]
	v_mfma_f32_16x16x32_bf16 v[36:39], v[140:143], v[172:175], v[36:39]
	ds_read_b128 v[136:139], v254 offset:18432
	ds_read_b128 v[140:143], v254 offset:19456
	s_cmp_lt_u32 s35, s17
	s_cbranch_scc0 .Lg0_O_sa
	s_sub_u32 s8, s8, 64
	s_subb_u32 s9, s9, 0
	s_cmp_gt_i32 s36, 0
	s_cselect_b32 s12, -1, 4
	s_add_i32 s12, s12, s36
	s_lshl_b32 s12, s12, 15
	s_add_i32 s12, s12, s16
	s_cmp_gt_i32 s36, 1
	s_cselect_b32 s10, -2, 3
	s_add_i32 s10, s10, s36
	s_lshl_b32 s10, s10, 15
	s_add_i32 s10, s10, s16
	s_mov_b32 m0, s10
	v_lshl_add_u64 v[168:169], v[160:161], 0, s[8:9]
	global_load_lds_dwordx4 v[168:169], off
	s_mov_b32 m0, s12
	v_lshl_add_u64 v[168:169], v[168:169], 0, 64
	global_load_lds_dwordx4 v[168:169], off
	s_add_u32 m0, s10, 0x2000
	v_lshl_add_u64 v[168:169], v[158:159], 0, s[8:9]
	global_load_lds_dwordx4 v[168:169], off
	s_add_u32 m0, s12, 0x2000
	v_lshl_add_u64 v[168:169], v[168:169], 0, 64
	global_load_lds_dwordx4 v[168:169], off
	s_add_u32 m0, s10, 0x4000
	v_lshl_add_u64 v[168:169], v[156:157], 0, s[8:9]
	global_load_lds_dwordx4 v[168:169], off
	s_add_u32 m0, s12, 0x4000
	v_lshl_add_u64 v[168:169], v[168:169], 0, 64
	global_load_lds_dwordx4 v[168:169], off
	s_add_u32 m0, s10, 0x6000
	v_lshl_add_u64 v[168:169], v[154:155], 0, s[8:9]
	global_load_lds_dwordx4 v[168:169], off
	s_add_u32 m0, s12, 0x6000
	v_lshl_add_u64 v[168:169], v[168:169], 0, 64
	global_load_lds_dwordx4 v[168:169], off
	s_add_u32 s8, s8, 64
	s_addc_u32 s9, s9, 0
.Lg0_O_sa:
	ds_read_b128 v[168:171], v152 offset:2048
	ds_read_b128 v[172:175], v152 offset:3072
	s_waitcnt lgkmcnt(4)
	v_mfma_f32_16x16x32_bf16 v[124:127], v[128:131], v[148:151], v[124:127]
	v_mfma_f32_16x16x32_bf16 v[120:123], v[132:135], v[148:151], v[120:123]
	v_mfma_f32_16x16x32_bf16 v[108:111], v[128:131], v[144:147], v[108:111]
	v_mfma_f32_16x16x32_bf16 v[104:107], v[132:135], v[144:147], v[104:107]
	s_waitcnt lgkmcnt(2)
	v_mfma_f32_16x16x32_bf16 v[116:119], v[136:139], v[148:151], v[116:119]
	v_mfma_f32_16x16x32_bf16 v[112:115], v[140:143], v[148:151], v[112:115]
	v_mfma_f32_16x16x32_bf16 v[100:103], v[136:139], v[144:147], v[100:103]
	v_mfma_f32_16x16x32_bf16 v[96:99], v[140:143], v[144:147], v[96:99]
	s_waitcnt lgkmcnt(0)
	v_mfma_f32_16x16x32_bf16 v[92:95], v[128:131], v[168:171], v[92:95]
	ds_read_b128 v[144:147], v152 offset:4096
	ds_read_b128 v[148:151], v152 offset:5120
	v_mfma_f32_16x16x32_bf16 v[88:91], v[132:135], v[168:171], v[88:91]
	v_mfma_f32_16x16x32_bf16 v[84:87], v[136:139], v[168:171], v[84:87]
	v_mfma_f32_16x16x32_bf16 v[80:83], v[140:143], v[168:171], v[80:83]
	v_mfma_f32_16x16x32_bf16 v[76:79], v[128:131], v[172:175], v[76:79]
	v_mfma_f32_16x16x32_bf16 v[72:75], v[132:135], v[172:175], v[72:75]
	v_mfma_f32_16x16x32_bf16 v[68:71], v[136:139], v[172:175], v[68:71]
	v_mfma_f32_16x16x32_bf16 v[64:67], v[140:143], v[172:175], v[64:67]
	s_cmp_lt_u32 s35, s11
	s_cbranch_scc0 .Lg0_O_sb
	s_sub_u32 s8, s8, 64
	s_subb_u32 s9, s9, 0
	s_cmp_gt_i32 s36, 0
	s_cselect_b32 s12, -1, 4
	s_add_i32 s12, s12, s36
	s_lshl_b32 s12, s12, 15
	s_add_i32 s12, s12, s16
	s_cmp_gt_i32 s36, 1
	s_cselect_b32 s10, -2, 3
	s_add_i32 s10, s10, s36
	s_lshl_b32 s10, s10, 15
	s_add_i32 s10, s10, s16
	s_mov_b32 m0, s10
	v_lshl_add_u64 v[168:169], v[160:161], 0, s[8:9]
	global_load_lds_dwordx4 v[168:169], off
	s_mov_b32 m0, s12
	v_lshl_add_u64 v[168:169], v[168:169], 0, 64
	global_load_lds_dwordx4 v[168:169], off
	s_add_u32 m0, s10, 0x2000
	v_lshl_add_u64 v[168:169], v[158:159], 0, s[8:9]
	global_load_lds_dwordx4 v[168:169], off
	s_add_u32 m0, s12, 0x2000
	v_lshl_add_u64 v[168:169], v[168:169], 0, 64
	global_load_lds_dwordx4 v[168:169], off
	s_add_u32 m0, s10, 0x4000
	v_lshl_add_u64 v[168:169], v[156:157], 0, s[8:9]
	global_load_lds_dwordx4 v[168:169], off
	s_add_u32 m0, s12, 0x4000
	v_lshl_add_u64 v[168:169], v[168:169], 0, 64
	global_load_lds_dwordx4 v[168:169], off
	s_add_u32 m0, s10, 0x6000
	v_lshl_add_u64 v[168:169], v[154:155], 0, s[8:9]
	global_load_lds_dwordx4 v[168:169], off
	s_add_u32 m0, s12, 0x6000
	v_lshl_add_u64 v[168:169], v[168:169], 0, 64
	global_load_lds_dwordx4 v[168:169], off
	s_add_u32 s8, s8, 64
	s_addc_u32 s9, s9, 0
.Lg0_O_sb:
	s_waitcnt lgkmcnt(0)
	v_mfma_f32_16x16x32_bf16 v[60:63], v[128:131], v[144:147], v[60:63]
	ds_read_b128 v[168:171], v152 offset:6144
	ds_read_b128 v[172:175], v152 offset:7168
	s_add_i32 s10, s36, 1
	v_mfma_f32_16x16x32_bf16 v[56:59], v[132:135], v[144:147], v[56:59]
	s_cmp_lg_u32 s10, 5
	s_cselect_b32 s36, s10, 0
	v_mfma_f32_16x16x32_bf16 v[52:55], v[136:139], v[144:147], v[52:55]
	s_add_i32 s35, s35, 1
	s_add_u32 s8, s8, 64
	v_mfma_f32_16x16x32_bf16 v[48:51], v[140:143], v[144:147], v[48:51]
	s_addc_u32 s9, s9, 0
	s_lshl_b32 s10, s36, 15
	v_mfma_f32_16x16x32_bf16 v[44:47], v[128:131], v[148:151], v[44:47]
	v_or_b32_e32 v254, s10, v165
	v_mfma_f32_16x16x32_bf16 v[40:43], v[132:135], v[148:151], v[40:43]
	v_add_u32_e32 v254, v254, v162
	v_mfma_f32_16x16x32_bf16 v[32:35], v[136:139], v[148:151], v[32:35]
	v_add_u32_e32 v152, s10, v164
	v_mfma_f32_16x16x32_bf16 v[28:31], v[140:143], v[148:151], v[28:31]
	v_add_u32_e32 v152, v152, v162
	s_cmp_lt_u32 s35, 29
	s_cbranch_scc0 .Lg0_Ot
	s_cmp_lt_u32 s35, 4
	s_cbranch_scc1 .Lg0_O_early
	s_waitcnt vmcnt(9)
	s_branch .Lg0_O_wd
.Lg0_O_early:
	s_waitcnt vmcnt(12)
.Lg0_O_wd:
	s_branch .Lg0_E
.Lg0_Et:
	s_cmp_eq_u32 s35, 29
	s_cbranch_scc0 .Lg0_Et0
	s_waitcnt vmcnt(8)
	s_branch .Lg0_Ew

.Lg0_Ot:
	s_cmp_eq_u32 s35, 32
	s_cbranch_scc1 .Lg0_X
	s_waitcnt vmcnt(1)
	s_branch .Lg0_E

.Lg1_E:
	s_waitcnt lgkmcnt(0)
	s_barrier
	ds_read_b128 v[246:249], v254 offset:16384
	ds_read_b128 v[250:253], v254 offset:17408
	ds_read_b128 v[150:153], v64
	ds_read_b128 v[146:149], v64 offset:1024
	v_mfma_f32_16x16x32_bf16 v[28:31], v[130:133], v[200:203], v[28:31]
	v_mfma_f32_16x16x32_bf16 v[24:27], v[134:137], v[200:203], v[24:27]
	v_mfma_f32_16x16x32_bf16 v[20:23], v[138:141], v[200:203], v[20:23]
	v_mfma_f32_16x16x32_bf16 v[16:19], v[142:145], v[200:203], v[16:19]
	v_mfma_f32_16x16x32_bf16 v[12:15], v[130:133], v[204:207], v[12:15]
	v_mfma_f32_16x16x32_bf16 v[8:11], v[134:137], v[204:207], v[8:11]
	v_mfma_f32_16x16x32_bf16 v[4:7], v[138:141], v[204:207], v[4:7]
	v_mfma_f32_16x16x32_bf16 v[0:3], v[142:145], v[204:207], v[0:3]
	ds_read_b128 v[138:141], v254 offset:18432
	ds_read_b128 v[142:145], v254 offset:19456
	ds_read_b128 v[200:203], v64 offset:2048
	ds_read_b128 v[204:207], v64 offset:3072
	s_waitcnt lgkmcnt(4)
	v_mfma_f32_16x16x32_bf16 v[126:129], v[246:249], v[150:153], v[126:129]
	v_mfma_f32_16x16x32_bf16 v[122:125], v[250:253], v[150:153], v[122:125]
	v_mfma_f32_16x16x32_bf16 v[110:113], v[246:249], v[146:149], v[110:113]
	v_mfma_f32_16x16x32_bf16 v[106:109], v[250:253], v[146:149], v[106:109]
	s_waitcnt lgkmcnt(2)
	v_mfma_f32_16x16x32_bf16 v[118:121], v[138:141], v[150:153], v[118:121]
	v_mfma_f32_16x16x32_bf16 v[114:117], v[142:145], v[150:153], v[114:117]
	v_mfma_f32_16x16x32_bf16 v[102:105], v[138:141], v[146:149], v[102:105]
	v_mfma_f32_16x16x32_bf16 v[98:101], v[142:145], v[146:149], v[98:101]
	s_waitcnt lgkmcnt(0)
	v_mfma_f32_16x16x32_bf16 v[94:97], v[246:249], v[200:203], v[94:97]
	ds_read_b128 v[146:149], v64 offset:4096
	ds_read_b128 v[150:153], v64 offset:5120
	v_mfma_f32_16x16x32_bf16 v[90:93], v[250:253], v[200:203], v[90:93]
	v_mfma_f32_16x16x32_bf16 v[86:89], v[138:141], v[200:203], v[86:89]
	v_mfma_f32_16x16x32_bf16 v[82:85], v[142:145], v[200:203], v[82:85]
	v_mfma_f32_16x16x32_bf16 v[78:81], v[246:249], v[204:207], v[78:81]
	v_mfma_f32_16x16x32_bf16 v[74:77], v[250:253], v[204:207], v[74:77]
	v_mfma_f32_16x16x32_bf16 v[70:73], v[138:141], v[204:207], v[70:73]
	v_mfma_f32_16x16x32_bf16 v[66:69], v[142:145], v[204:207], v[66:69]
	s_waitcnt lgkmcnt(0)
	v_mfma_f32_16x16x32_bf16 v[60:63], v[246:249], v[146:149], v[60:63]
	ds_read_b128 v[200:203], v64 offset:6144
	ds_read_b128 v[204:207], v64 offset:7168
	s_add_i32 s26, s60, 1
	v_mfma_f32_16x16x32_bf16 v[56:59], v[250:253], v[146:149], v[56:59]
	s_cmp_lg_u32 s26, 5
	s_cselect_b32 s60, s26, 0
	v_mfma_f32_16x16x32_bf16 v[52:55], v[138:141], v[146:149], v[52:55]
	s_add_i32 s25, s25, 1
	s_add_u32 s0, s0, 64
	v_mfma_f32_16x16x32_bf16 v[48:51], v[142:145], v[146:149], v[48:51]
	s_addc_u32 s1, s1, 0
	s_lshl_b32 s26, s60, 15
	v_mfma_f32_16x16x32_bf16 v[44:47], v[246:249], v[150:153], v[44:47]
	v_or_b32_e32 v254, s26, v198
	v_mfma_f32_16x16x32_bf16 v[40:43], v[250:253], v[150:153], v[40:43]
	v_add_u32_e32 v254, v254, v196
	v_mfma_f32_16x16x32_bf16 v[36:39], v[138:141], v[150:153], v[36:39]
	v_add_u32_e32 v64, s26, v197
	v_mfma_f32_16x16x32_bf16 v[32:35], v[142:145], v[150:153], v[32:35]
	v_add_u32_e32 v64, v64, v196
	s_cmp_lt_u32 s25, 29
	s_cbranch_scc0 .Lg1_Et
	s_waitcnt vmcnt(8)
.Lg1_Ew:
.Lg1_O:
	s_waitcnt lgkmcnt(0)
	s_barrier
	ds_read_b128 v[130:133], v254 offset:16384
	ds_read_b128 v[134:137], v254 offset:17408
	ds_read_b128 v[150:153], v64
	ds_read_b128 v[146:149], v64 offset:1024
	v_mfma_f32_16x16x32_bf16 v[28:31], v[246:249], v[200:203], v[28:31]
	v_mfma_f32_16x16x32_bf16 v[24:27], v[250:253], v[200:203], v[24:27]
	v_mfma_f32_16x16x32_bf16 v[20:23], v[138:141], v[200:203], v[20:23]
	v_mfma_f32_16x16x32_bf16 v[16:19], v[142:145], v[200:203], v[16:19]
	v_mfma_f32_16x16x32_bf16 v[12:15], v[246:249], v[204:207], v[12:15]
	v_mfma_f32_16x16x32_bf16 v[8:11], v[250:253], v[204:207], v[8:11]
	v_mfma_f32_16x16x32_bf16 v[4:7], v[138:141], v[204:207], v[4:7]
	v_mfma_f32_16x16x32_bf16 v[0:3], v[142:145], v[204:207], v[0:3]
	ds_read_b128 v[138:141], v254 offset:18432
	ds_read_b128 v[142:145], v254 offset:19456
	s_cmp_lt_u32 s25, s37
	s_cbranch_scc0 .Lg1_O_sa
	s_sub_u32 s0, s0, 64
	s_subb_u32 s1, s1, 0
	s_cmp_gt_i32 s60, 0
	s_cselect_b32 s30, -1, 4
	s_add_i32 s30, s30, s60
	s_lshl_b32 s30, s30, 15
	s_add_i32 s30, s30, s36
	s_cmp_gt_i32 s60, 1
	s_cselect_b32 s26, -2, 3
	s_add_i32 s26, s26, s60
	s_lshl_b32 s26, s26, 15
	s_add_i32 s26, s26, s36
	s_mov_b32 m0, s26
	v_lshl_add_u64 v[200:201], v[164:165], 0, s[0:1]
	global_load_lds_dwordx4 v[200:201], off
	s_mov_b32 m0, s30
	v_lshl_add_u64 v[200:201], v[200:201], 0, 64
	global_load_lds_dwordx4 v[200:201], off
	s_add_u32 m0, s26, 0x2000
	v_lshl_add_u64 v[200:201], v[162:163], 0, s[0:1]
	global_load_lds_dwordx4 v[200:201], off
	s_add_u32 m0, s30, 0x2000
	v_lshl_add_u64 v[200:201], v[200:201], 0, 64
	global_load_lds_dwordx4 v[200:201], off
	s_add_u32 m0, s26, 0x4000
	v_lshl_add_u64 v[200:201], v[160:161], 0, s[0:1]
	global_load_lds_dwordx4 v[200:201], off
	s_add_u32 m0, s30, 0x4000
	v_lshl_add_u64 v[200:201], v[200:201], 0, 64
	global_load_lds_dwordx4 v[200:201], off
	s_add_u32 m0, s26, 0x6000
	v_lshl_add_u64 v[200:201], v[158:159], 0, s[0:1]
	global_load_lds_dwordx4 v[200:201], off
	s_add_u32 m0, s30, 0x6000
	v_lshl_add_u64 v[200:201], v[200:201], 0, 64
	global_load_lds_dwordx4 v[200:201], off
	s_add_u32 s0, s0, 64
	s_addc_u32 s1, s1, 0
.Lg1_O_sa:
	ds_read_b128 v[200:203], v64 offset:2048
	ds_read_b128 v[204:207], v64 offset:3072
	s_waitcnt lgkmcnt(4)
	v_mfma_f32_16x16x32_bf16 v[126:129], v[130:133], v[150:153], v[126:129]
	v_mfma_f32_16x16x32_bf16 v[122:125], v[134:137], v[150:153], v[122:125]
	v_mfma_f32_16x16x32_bf16 v[110:113], v[130:133], v[146:149], v[110:113]
	v_mfma_f32_16x16x32_bf16 v[106:109], v[134:137], v[146:149], v[106:109]
	s_waitcnt lgkmcnt(2)
	v_mfma_f32_16x16x32_bf16 v[118:121], v[138:141], v[150:153], v[118:121]
	v_mfma_f32_16x16x32_bf16 v[114:117], v[142:145], v[150:153], v[114:117]
	v_mfma_f32_16x16x32_bf16 v[102:105], v[138:141], v[146:149], v[102:105]
	v_mfma_f32_16x16x32_bf16 v[98:101], v[142:145], v[146:149], v[98:101]
	s_waitcnt lgkmcnt(0)
	v_mfma_f32_16x16x32_bf16 v[94:97], v[130:133], v[200:203], v[94:97]
	ds_read_b128 v[146:149], v64 offset:4096
	ds_read_b128 v[150:153], v64 offset:5120
	v_mfma_f32_16x16x32_bf16 v[90:93], v[134:137], v[200:203], v[90:93]
	v_mfma_f32_16x16x32_bf16 v[86:89], v[138:141], v[200:203], v[86:89]
	v_mfma_f32_16x16x32_bf16 v[82:85], v[142:145], v[200:203], v[82:85]
	v_mfma_f32_16x16x32_bf16 v[78:81], v[130:133], v[204:207], v[78:81]
	v_mfma_f32_16x16x32_bf16 v[74:77], v[134:137], v[204:207], v[74:77]
	v_mfma_f32_16x16x32_bf16 v[70:73], v[138:141], v[204:207], v[70:73]
	v_mfma_f32_16x16x32_bf16 v[66:69], v[142:145], v[204:207], v[66:69]
	s_cmp_lt_u32 s25, s27
	s_cbranch_scc0 .Lg1_O_sb
	s_sub_u32 s0, s0, 64
	s_subb_u32 s1, s1, 0
	s_cmp_gt_i32 s60, 0
	s_cselect_b32 s30, -1, 4
	s_add_i32 s30, s30, s60
	s_lshl_b32 s30, s30, 15
	s_add_i32 s30, s30, s36
	s_cmp_gt_i32 s60, 1
	s_cselect_b32 s26, -2, 3
	s_add_i32 s26, s26, s60
	s_lshl_b32 s26, s26, 15
	s_add_i32 s26, s26, s36
	s_mov_b32 m0, s26
	v_lshl_add_u64 v[200:201], v[164:165], 0, s[0:1]
	global_load_lds_dwordx4 v[200:201], off
	s_mov_b32 m0, s30
	v_lshl_add_u64 v[200:201], v[200:201], 0, 64
	global_load_lds_dwordx4 v[200:201], off
	s_add_u32 m0, s26, 0x2000
	v_lshl_add_u64 v[200:201], v[162:163], 0, s[0:1]
	global_load_lds_dwordx4 v[200:201], off
	s_add_u32 m0, s30, 0x2000
	v_lshl_add_u64 v[200:201], v[200:201], 0, 64
	global_load_lds_dwordx4 v[200:201], off
	s_add_u32 m0, s26, 0x4000
	v_lshl_add_u64 v[200:201], v[160:161], 0, s[0:1]
	global_load_lds_dwordx4 v[200:201], off
	s_add_u32 m0, s30, 0x4000
	v_lshl_add_u64 v[200:201], v[200:201], 0, 64
	global_load_lds_dwordx4 v[200:201], off
	s_add_u32 m0, s26, 0x6000
	v_lshl_add_u64 v[200:201], v[158:159], 0, s[0:1]
	global_load_lds_dwordx4 v[200:201], off
	s_add_u32 m0, s30, 0x6000
	v_lshl_add_u64 v[200:201], v[200:201], 0, 64
	global_load_lds_dwordx4 v[200:201], off
	s_add_u32 s0, s0, 64
	s_addc_u32 s1, s1, 0
.Lg1_O_sb:
	s_waitcnt lgkmcnt(0)
	v_mfma_f32_16x16x32_bf16 v[60:63], v[130:133], v[146:149], v[60:63]
	ds_read_b128 v[200:203], v64 offset:6144
	ds_read_b128 v[204:207], v64 offset:7168
	s_add_i32 s26, s60, 1
	v_mfma_f32_16x16x32_bf16 v[56:59], v[134:137], v[146:149], v[56:59]
	s_cmp_lg_u32 s26, 5
	s_cselect_b32 s60, s26, 0
	v_mfma_f32_16x16x32_bf16 v[52:55], v[138:141], v[146:149], v[52:55]
	s_add_i32 s25, s25, 1
	s_add_u32 s0, s0, 64
	v_mfma_f32_16x16x32_bf16 v[48:51], v[142:145], v[146:149], v[48:51]
	s_addc_u32 s1, s1, 0
	s_lshl_b32 s26, s60, 15
	v_mfma_f32_16x16x32_bf16 v[44:47], v[130:133], v[150:153], v[44:47]
	v_or_b32_e32 v254, s26, v198
	v_mfma_f32_16x16x32_bf16 v[40:43], v[134:137], v[150:153], v[40:43]
	v_add_u32_e32 v254, v254, v196
	v_mfma_f32_16x16x32_bf16 v[36:39], v[138:141], v[150:153], v[36:39]
	v_add_u32_e32 v64, s26, v197
	v_mfma_f32_16x16x32_bf16 v[32:35], v[142:145], v[150:153], v[32:35]
	v_add_u32_e32 v64, v64, v196
	s_cmp_lt_u32 s25, 29
	s_cbranch_scc0 .Lg1_Ot
	s_cmp_lt_u32 s25, 4
	s_cbranch_scc1 .Lg1_O_early
	s_waitcnt vmcnt(9)
	s_branch .Lg1_O_wd

.Lg1_O_wd:
	s_branch .Lg1_E
.Lg1_Et:
	s_cmp_eq_u32 s25, 29
	s_cbranch_scc0 .Lg1_Et0
	s_waitcnt vmcnt(8)
	s_branch .Lg1_Ew

.Lg1_Ot:
	s_cmp_eq_u32 s25, 32
	s_cbranch_scc1 .Lg1_X
	s_waitcnt vmcnt(1)
	s_branch .Lg1_E

.Lg2_E:
	s_waitcnt lgkmcnt(0)
	s_barrier
	ds_read_b128 v[246:249], v254 offset:16384
	ds_read_b128 v[250:253], v254 offset:17408
	ds_read_b128 v[150:153], v64
	ds_read_b128 v[146:149], v64 offset:1024
	v_mfma_f32_16x16x32_bf16 v[102:105], v[130:133], v[202:205], v[102:105]
	v_mfma_f32_16x16x32_bf16 v[70:73], v[134:137], v[202:205], v[70:73]
	v_mfma_f32_16x16x32_bf16 v[36:39], v[138:141], v[202:205], v[36:39]
	v_mfma_f32_16x16x32_bf16 v[4:7], v[142:145], v[202:205], v[4:7]
	v_mfma_f32_16x16x32_bf16 v[98:101], v[130:133], v[206:209], v[98:101]
	v_mfma_f32_16x16x32_bf16 v[66:69], v[134:137], v[206:209], v[66:69]
	v_mfma_f32_16x16x32_bf16 v[28:31], v[138:141], v[206:209], v[28:31]
	v_mfma_f32_16x16x32_bf16 v[0:3], v[142:145], v[206:209], v[0:3]
	ds_read_b128 v[138:141], v254 offset:18432
	ds_read_b128 v[142:145], v254 offset:19456
	ds_read_b128 v[202:205], v64 offset:2048
	ds_read_b128 v[206:209], v64 offset:3072
	s_waitcnt lgkmcnt(4)
	v_mfma_f32_16x16x32_bf16 v[126:129], v[246:249], v[150:153], v[126:129]
	v_mfma_f32_16x16x32_bf16 v[94:97], v[250:253], v[150:153], v[94:97]
	v_mfma_f32_16x16x32_bf16 v[122:125], v[246:249], v[146:149], v[122:125]
	v_mfma_f32_16x16x32_bf16 v[90:93], v[250:253], v[146:149], v[90:93]
	s_waitcnt lgkmcnt(2)
	v_mfma_f32_16x16x32_bf16 v[60:63], v[138:141], v[150:153], v[60:63]
	v_mfma_f32_16x16x32_bf16 v[32:35], v[142:145], v[150:153], v[32:35]
	v_mfma_f32_16x16x32_bf16 v[56:59], v[138:141], v[146:149], v[56:59]
	v_mfma_f32_16x16x32_bf16 v[24:27], v[142:145], v[146:149], v[24:27]
	s_waitcnt lgkmcnt(0)
	v_mfma_f32_16x16x32_bf16 v[118:121], v[246:249], v[202:205], v[118:121]
	ds_read_b128 v[146:149], v64 offset:4096
	ds_read_b128 v[150:153], v64 offset:5120
	v_mfma_f32_16x16x32_bf16 v[86:89], v[250:253], v[202:205], v[86:89]
	v_mfma_f32_16x16x32_bf16 v[52:55], v[138:141], v[202:205], v[52:55]
	v_mfma_f32_16x16x32_bf16 v[20:23], v[142:145], v[202:205], v[20:23]
	v_mfma_f32_16x16x32_bf16 v[114:117], v[246:249], v[206:209], v[114:117]
	v_mfma_f32_16x16x32_bf16 v[82:85], v[250:253], v[206:209], v[82:85]
	v_mfma_f32_16x16x32_bf16 v[48:51], v[138:141], v[206:209], v[48:51]
	v_mfma_f32_16x16x32_bf16 v[16:19], v[142:145], v[206:209], v[16:19]
	s_waitcnt lgkmcnt(0)
	v_mfma_f32_16x16x32_bf16 v[110:113], v[246:249], v[146:149], v[110:113]
	ds_read_b128 v[202:205], v64 offset:6144
	ds_read_b128 v[206:209], v64 offset:7168
	s_add_i32 s26, s79, 1
	v_mfma_f32_16x16x32_bf16 v[78:81], v[250:253], v[146:149], v[78:81]
	s_cmp_lg_u32 s26, 5
	s_cselect_b32 s79, s26, 0
	v_mfma_f32_16x16x32_bf16 v[44:47], v[138:141], v[146:149], v[44:47]
	s_add_i32 s25, s25, 1
	s_add_u32 s0, s0, 64
	v_mfma_f32_16x16x32_bf16 v[12:15], v[142:145], v[146:149], v[12:15]
	s_addc_u32 s1, s1, 0
	s_lshl_b32 s26, s79, 15
	v_mfma_f32_16x16x32_bf16 v[106:109], v[246:249], v[150:153], v[106:109]
	v_or_b32_e32 v254, s26, v199
	v_mfma_f32_16x16x32_bf16 v[74:77], v[250:253], v[150:153], v[74:77]
	v_add_u32_e32 v254, v254, v197
	v_mfma_f32_16x16x32_bf16 v[40:43], v[138:141], v[150:153], v[40:43]
	v_add_u32_e32 v64, s26, v198
	v_mfma_f32_16x16x32_bf16 v[8:11], v[142:145], v[150:153], v[8:11]
	v_add_u32_e32 v64, v64, v197
	s_cmp_lt_u32 s25, 29
	s_cbranch_scc0 .Lg2_Et
	s_waitcnt vmcnt(8)
.Lg2_Ew:
.Lg2_O:
	s_waitcnt lgkmcnt(0)
	s_barrier
	ds_read_b128 v[130:133], v254 offset:16384
	ds_read_b128 v[134:137], v254 offset:17408
	ds_read_b128 v[150:153], v64
	ds_read_b128 v[146:149], v64 offset:1024
	v_mfma_f32_16x16x32_bf16 v[102:105], v[246:249], v[202:205], v[102:105]
	v_mfma_f32_16x16x32_bf16 v[70:73], v[250:253], v[202:205], v[70:73]
	v_mfma_f32_16x16x32_bf16 v[36:39], v[138:141], v[202:205], v[36:39]
	v_mfma_f32_16x16x32_bf16 v[4:7], v[142:145], v[202:205], v[4:7]
	v_mfma_f32_16x16x32_bf16 v[98:101], v[246:249], v[206:209], v[98:101]
	v_mfma_f32_16x16x32_bf16 v[66:69], v[250:253], v[206:209], v[66:69]
	v_mfma_f32_16x16x32_bf16 v[28:31], v[138:141], v[206:209], v[28:31]
	v_mfma_f32_16x16x32_bf16 v[0:3], v[142:145], v[206:209], v[0:3]
	ds_read_b128 v[138:141], v254 offset:18432
	ds_read_b128 v[142:145], v254 offset:19456
	s_cmp_lt_u32 s25, s37
	s_cbranch_scc0 .Lg2_O_sa
	s_sub_u32 s0, s0, 64
	s_subb_u32 s1, s1, 0
	s_cmp_gt_i32 s79, 0
	s_cselect_b32 s28, -1, 4
	s_add_i32 s28, s28, s79
	s_lshl_b32 s28, s28, 15
	s_add_i32 s28, s28, s36
	s_cmp_gt_i32 s79, 1
	s_cselect_b32 s26, -2, 3
	s_add_i32 s26, s26, s79
	s_lshl_b32 s26, s26, 15
	s_add_i32 s26, s26, s36
	s_mov_b32 m0, s26
	v_lshl_add_u64 v[202:203], v[164:165], 0, s[0:1]
	global_load_lds_dwordx4 v[202:203], off
	s_mov_b32 m0, s28
	v_lshl_add_u64 v[202:203], v[202:203], 0, 64
	global_load_lds_dwordx4 v[202:203], off
	s_add_u32 m0, s26, 0x2000
	v_lshl_add_u64 v[202:203], v[162:163], 0, s[0:1]
	global_load_lds_dwordx4 v[202:203], off
	s_add_u32 m0, s28, 0x2000
	v_lshl_add_u64 v[202:203], v[202:203], 0, 64
	global_load_lds_dwordx4 v[202:203], off
	s_add_u32 m0, s26, 0x4000
	v_lshl_add_u64 v[202:203], v[160:161], 0, s[0:1]
	global_load_lds_dwordx4 v[202:203], off
	s_add_u32 m0, s28, 0x4000
	v_lshl_add_u64 v[202:203], v[202:203], 0, 64
	global_load_lds_dwordx4 v[202:203], off
	s_add_u32 m0, s26, 0x6000
	v_lshl_add_u64 v[202:203], v[158:159], 0, s[0:1]
	global_load_lds_dwordx4 v[202:203], off
	s_add_u32 m0, s28, 0x6000
	v_lshl_add_u64 v[202:203], v[202:203], 0, 64
	global_load_lds_dwordx4 v[202:203], off
	s_add_u32 s0, s0, 64
	s_addc_u32 s1, s1, 0
.Lg2_O_sa:
	ds_read_b128 v[202:205], v64 offset:2048
	ds_read_b128 v[206:209], v64 offset:3072
	s_waitcnt lgkmcnt(4)
	v_mfma_f32_16x16x32_bf16 v[126:129], v[130:133], v[150:153], v[126:129]
	v_mfma_f32_16x16x32_bf16 v[94:97], v[134:137], v[150:153], v[94:97]
	v_mfma_f32_16x16x32_bf16 v[122:125], v[130:133], v[146:149], v[122:125]
	v_mfma_f32_16x16x32_bf16 v[90:93], v[134:137], v[146:149], v[90:93]
	s_waitcnt lgkmcnt(2)
	v_mfma_f32_16x16x32_bf16 v[60:63], v[138:141], v[150:153], v[60:63]
	v_mfma_f32_16x16x32_bf16 v[32:35], v[142:145], v[150:153], v[32:35]
	v_mfma_f32_16x16x32_bf16 v[56:59], v[138:141], v[146:149], v[56:59]
	v_mfma_f32_16x16x32_bf16 v[24:27], v[142:145], v[146:149], v[24:27]
	s_waitcnt lgkmcnt(0)
	v_mfma_f32_16x16x32_bf16 v[118:121], v[130:133], v[202:205], v[118:121]
	ds_read_b128 v[146:149], v64 offset:4096
	ds_read_b128 v[150:153], v64 offset:5120
	v_mfma_f32_16x16x32_bf16 v[86:89], v[134:137], v[202:205], v[86:89]
	v_mfma_f32_16x16x32_bf16 v[52:55], v[138:141], v[202:205], v[52:55]
	v_mfma_f32_16x16x32_bf16 v[20:23], v[142:145], v[202:205], v[20:23]
	v_mfma_f32_16x16x32_bf16 v[114:117], v[130:133], v[206:209], v[114:117]
	v_mfma_f32_16x16x32_bf16 v[82:85], v[134:137], v[206:209], v[82:85]
	v_mfma_f32_16x16x32_bf16 v[48:51], v[138:141], v[206:209], v[48:51]
	v_mfma_f32_16x16x32_bf16 v[16:19], v[142:145], v[206:209], v[16:19]
	s_cmp_lt_u32 s25, s27
	s_cbranch_scc0 .Lg2_O_sb
	s_sub_u32 s0, s0, 64
	s_subb_u32 s1, s1, 0
	s_cmp_gt_i32 s79, 0
	s_cselect_b32 s28, -1, 4
	s_add_i32 s28, s28, s79
	s_lshl_b32 s28, s28, 15
	s_add_i32 s28, s28, s36
	s_cmp_gt_i32 s79, 1
	s_cselect_b32 s26, -2, 3
	s_add_i32 s26, s26, s79
	s_lshl_b32 s26, s26, 15
	s_add_i32 s26, s26, s36
	s_mov_b32 m0, s26
	v_lshl_add_u64 v[202:203], v[164:165], 0, s[0:1]
	global_load_lds_dwordx4 v[202:203], off
	s_mov_b32 m0, s28
	v_lshl_add_u64 v[202:203], v[202:203], 0, 64
	global_load_lds_dwordx4 v[202:203], off
	s_add_u32 m0, s26, 0x2000
	v_lshl_add_u64 v[202:203], v[162:163], 0, s[0:1]
	global_load_lds_dwordx4 v[202:203], off
	s_add_u32 m0, s28, 0x2000
	v_lshl_add_u64 v[202:203], v[202:203], 0, 64
	global_load_lds_dwordx4 v[202:203], off
	s_add_u32 m0, s26, 0x4000
	v_lshl_add_u64 v[202:203], v[160:161], 0, s[0:1]
	global_load_lds_dwordx4 v[202:203], off
	s_add_u32 m0, s28, 0x4000
	v_lshl_add_u64 v[202:203], v[202:203], 0, 64
	global_load_lds_dwordx4 v[202:203], off
	s_add_u32 m0, s26, 0x6000
	v_lshl_add_u64 v[202:203], v[158:159], 0, s[0:1]
	global_load_lds_dwordx4 v[202:203], off
	s_add_u32 m0, s28, 0x6000
	v_lshl_add_u64 v[202:203], v[202:203], 0, 64
	global_load_lds_dwordx4 v[202:203], off
	s_add_u32 s0, s0, 64
	s_addc_u32 s1, s1, 0
.Lg2_O_sb:
	s_waitcnt lgkmcnt(0)
	v_mfma_f32_16x16x32_bf16 v[110:113], v[130:133], v[146:149], v[110:113]
	ds_read_b128 v[202:205], v64 offset:6144
	ds_read_b128 v[206:209], v64 offset:7168
	s_add_i32 s26, s79, 1
	v_mfma_f32_16x16x32_bf16 v[78:81], v[134:137], v[146:149], v[78:81]
	s_cmp_lg_u32 s26, 5
	s_cselect_b32 s79, s26, 0
	v_mfma_f32_16x16x32_bf16 v[44:47], v[138:141], v[146:149], v[44:47]
	s_add_i32 s25, s25, 1
	s_add_u32 s0, s0, 64
	v_mfma_f32_16x16x32_bf16 v[12:15], v[142:145], v[146:149], v[12:15]
	s_addc_u32 s1, s1, 0
	s_lshl_b32 s26, s79, 15
	v_mfma_f32_16x16x32_bf16 v[106:109], v[130:133], v[150:153], v[106:109]
	v_or_b32_e32 v254, s26, v199
	v_mfma_f32_16x16x32_bf16 v[74:77], v[134:137], v[150:153], v[74:77]
	v_add_u32_e32 v254, v254, v197
	v_mfma_f32_16x16x32_bf16 v[40:43], v[138:141], v[150:153], v[40:43]
	v_add_u32_e32 v64, s26, v198
	v_mfma_f32_16x16x32_bf16 v[8:11], v[142:145], v[150:153], v[8:11]
	v_add_u32_e32 v64, v64, v197
	s_cmp_lt_u32 s25, 29
	s_cbranch_scc0 .Lg2_Ot
	s_cmp_lt_u32 s25, 4
	s_cbranch_scc1 .Lg2_O_early
	s_waitcnt vmcnt(9)
	s_branch .Lg2_O_wd

.Lg2_O_wd:
	s_branch .Lg2_E
.Lg2_Et:
	s_cmp_eq_u32 s25, 29
	s_cbranch_scc0 .Lg2_Et0
	s_waitcnt vmcnt(8)
	s_branch .Lg2_Ew

.Lg3_E:
	s_waitcnt lgkmcnt(0)
	s_barrier
	ds_read_b128 v[246:249], v254 offset:16384
	ds_read_b128 v[250:253], v254 offset:17408
	ds_read_b128 v[150:153], v64
	ds_read_b128 v[146:149], v64 offset:1024
	v_mfma_f32_16x16x32_bf16 v[28:31], v[130:133], v[202:205], v[28:31]
	v_mfma_f32_16x16x32_bf16 v[24:27], v[134:137], v[202:205], v[24:27]
	v_mfma_f32_16x16x32_bf16 v[20:23], v[138:141], v[202:205], v[20:23]
	v_mfma_f32_16x16x32_bf16 v[16:19], v[142:145], v[202:205], v[16:19]
	v_mfma_f32_16x16x32_bf16 v[12:15], v[130:133], v[206:209], v[12:15]
	v_mfma_f32_16x16x32_bf16 v[8:11], v[134:137], v[206:209], v[8:11]
	v_mfma_f32_16x16x32_bf16 v[4:7], v[138:141], v[206:209], v[4:7]
	v_mfma_f32_16x16x32_bf16 v[0:3], v[142:145], v[206:209], v[0:3]
	ds_read_b128 v[138:141], v254 offset:18432
	ds_read_b128 v[142:145], v254 offset:19456
	ds_read_b128 v[202:205], v64 offset:2048
	ds_read_b128 v[206:209], v64 offset:3072
	s_waitcnt lgkmcnt(4)
	v_mfma_f32_16x16x32_bf16 v[126:129], v[246:249], v[150:153], v[126:129]
	v_mfma_f32_16x16x32_bf16 v[122:125], v[250:253], v[150:153], v[122:125]
	v_mfma_f32_16x16x32_bf16 v[110:113], v[246:249], v[146:149], v[110:113]
	v_mfma_f32_16x16x32_bf16 v[106:109], v[250:253], v[146:149], v[106:109]
	s_waitcnt lgkmcnt(2)
	v_mfma_f32_16x16x32_bf16 v[118:121], v[138:141], v[150:153], v[118:121]
	v_mfma_f32_16x16x32_bf16 v[114:117], v[142:145], v[150:153], v[114:117]
	v_mfma_f32_16x16x32_bf16 v[102:105], v[138:141], v[146:149], v[102:105]
	v_mfma_f32_16x16x32_bf16 v[98:101], v[142:145], v[146:149], v[98:101]
	s_waitcnt lgkmcnt(0)
	v_mfma_f32_16x16x32_bf16 v[94:97], v[246:249], v[202:205], v[94:97]
	ds_read_b128 v[146:149], v64 offset:4096
	ds_read_b128 v[150:153], v64 offset:5120
	v_mfma_f32_16x16x32_bf16 v[90:93], v[250:253], v[202:205], v[90:93]
	v_mfma_f32_16x16x32_bf16 v[86:89], v[138:141], v[202:205], v[86:89]
	v_mfma_f32_16x16x32_bf16 v[82:85], v[142:145], v[202:205], v[82:85]
	v_mfma_f32_16x16x32_bf16 v[78:81], v[246:249], v[206:209], v[78:81]
	v_mfma_f32_16x16x32_bf16 v[74:77], v[250:253], v[206:209], v[74:77]
	v_mfma_f32_16x16x32_bf16 v[70:73], v[138:141], v[206:209], v[70:73]
	v_mfma_f32_16x16x32_bf16 v[66:69], v[142:145], v[206:209], v[66:69]
	s_waitcnt lgkmcnt(0)
	v_mfma_f32_16x16x32_bf16 v[60:63], v[246:249], v[146:149], v[60:63]
	ds_read_b128 v[202:205], v64 offset:6144
	ds_read_b128 v[206:209], v64 offset:7168
	s_add_i32 s26, s75, 1
	v_mfma_f32_16x16x32_bf16 v[56:59], v[250:253], v[146:149], v[56:59]
	s_cmp_lg_u32 s26, 5
	s_cselect_b32 s75, s26, 0
	v_mfma_f32_16x16x32_bf16 v[52:55], v[138:141], v[146:149], v[52:55]
	s_add_i32 s25, s25, 1
	s_add_u32 s28, s28, 64
	v_mfma_f32_16x16x32_bf16 v[48:51], v[142:145], v[146:149], v[48:51]
	s_addc_u32 s29, s29, 0
	s_lshl_b32 s26, s75, 15
	v_mfma_f32_16x16x32_bf16 v[44:47], v[246:249], v[150:153], v[44:47]
	v_or_b32_e32 v254, s26, v199
	v_mfma_f32_16x16x32_bf16 v[40:43], v[250:253], v[150:153], v[40:43]
	v_add_u32_e32 v254, v254, v197
	v_mfma_f32_16x16x32_bf16 v[36:39], v[138:141], v[150:153], v[36:39]
	v_add_u32_e32 v64, s26, v198
	v_mfma_f32_16x16x32_bf16 v[32:35], v[142:145], v[150:153], v[32:35]
	v_add_u32_e32 v64, v64, v197
	s_cmp_lt_u32 s25, 29
	s_cbranch_scc0 .Lg3_Et
	s_waitcnt vmcnt(8)
.Lg3_Ew:
.Lg3_O:
	s_waitcnt lgkmcnt(0)
	s_barrier
	ds_read_b128 v[130:133], v254 offset:16384
	ds_read_b128 v[134:137], v254 offset:17408
	ds_read_b128 v[150:153], v64
	ds_read_b128 v[146:149], v64 offset:1024
	v_mfma_f32_16x16x32_bf16 v[28:31], v[246:249], v[202:205], v[28:31]
	v_mfma_f32_16x16x32_bf16 v[24:27], v[250:253], v[202:205], v[24:27]
	v_mfma_f32_16x16x32_bf16 v[20:23], v[138:141], v[202:205], v[20:23]
	v_mfma_f32_16x16x32_bf16 v[16:19], v[142:145], v[202:205], v[16:19]
	v_mfma_f32_16x16x32_bf16 v[12:15], v[246:249], v[206:209], v[12:15]
	v_mfma_f32_16x16x32_bf16 v[8:11], v[250:253], v[206:209], v[8:11]
	v_mfma_f32_16x16x32_bf16 v[4:7], v[138:141], v[206:209], v[4:7]
	v_mfma_f32_16x16x32_bf16 v[0:3], v[142:145], v[206:209], v[0:3]
	ds_read_b128 v[138:141], v254 offset:18432
	ds_read_b128 v[142:145], v254 offset:19456
	s_cmp_lt_u32 s25, s45
	s_cbranch_scc0 .Lg3_O_sa
	s_sub_u32 s28, s28, 64
	s_subb_u32 s29, s29, 0
	s_cmp_gt_i32 s75, 0
	s_cselect_b32 s30, -1, 4
	s_add_i32 s30, s30, s75
	s_lshl_b32 s30, s30, 15
	s_add_i32 s30, s30, s44
	s_cmp_gt_i32 s75, 1
	s_cselect_b32 s26, -2, 3
	s_add_i32 s26, s26, s75
	s_lshl_b32 s26, s26, 15
	s_add_i32 s26, s26, s44
	s_mov_b32 m0, s26
	v_lshl_add_u64 v[202:203], v[164:165], 0, s[28:29]
	global_load_lds_dwordx4 v[202:203], off
	s_mov_b32 m0, s30
	v_lshl_add_u64 v[202:203], v[202:203], 0, 64
	global_load_lds_dwordx4 v[202:203], off
	s_add_u32 m0, s26, 0x2000
	v_lshl_add_u64 v[202:203], v[162:163], 0, s[28:29]
	global_load_lds_dwordx4 v[202:203], off
	s_add_u32 m0, s30, 0x2000
	v_lshl_add_u64 v[202:203], v[202:203], 0, 64
	global_load_lds_dwordx4 v[202:203], off
	s_add_u32 m0, s26, 0x4000
	v_lshl_add_u64 v[202:203], v[160:161], 0, s[28:29]
	global_load_lds_dwordx4 v[202:203], off
	s_add_u32 m0, s30, 0x4000
	v_lshl_add_u64 v[202:203], v[202:203], 0, 64
	global_load_lds_dwordx4 v[202:203], off
	s_add_u32 m0, s26, 0x6000
	v_lshl_add_u64 v[202:203], v[158:159], 0, s[28:29]
	global_load_lds_dwordx4 v[202:203], off
	s_add_u32 m0, s30, 0x6000
	v_lshl_add_u64 v[202:203], v[202:203], 0, 64
	global_load_lds_dwordx4 v[202:203], off
	s_add_u32 s28, s28, 64
	s_addc_u32 s29, s29, 0
.Lg3_O_sa:
	ds_read_b128 v[202:205], v64 offset:2048
	ds_read_b128 v[206:209], v64 offset:3072
	s_waitcnt lgkmcnt(4)
	v_mfma_f32_16x16x32_bf16 v[126:129], v[130:133], v[150:153], v[126:129]
	v_mfma_f32_16x16x32_bf16 v[122:125], v[134:137], v[150:153], v[122:125]
	v_mfma_f32_16x16x32_bf16 v[110:113], v[130:133], v[146:149], v[110:113]
	v_mfma_f32_16x16x32_bf16 v[106:109], v[134:137], v[146:149], v[106:109]
	s_waitcnt lgkmcnt(2)
	v_mfma_f32_16x16x32_bf16 v[118:121], v[138:141], v[150:153], v[118:121]
	v_mfma_f32_16x16x32_bf16 v[114:117], v[142:145], v[150:153], v[114:117]
	v_mfma_f32_16x16x32_bf16 v[102:105], v[138:141], v[146:149], v[102:105]
	v_mfma_f32_16x16x32_bf16 v[98:101], v[142:145], v[146:149], v[98:101]
	s_waitcnt lgkmcnt(0)
	v_mfma_f32_16x16x32_bf16 v[94:97], v[130:133], v[202:205], v[94:97]
	ds_read_b128 v[146:149], v64 offset:4096
	ds_read_b128 v[150:153], v64 offset:5120
	v_mfma_f32_16x16x32_bf16 v[90:93], v[134:137], v[202:205], v[90:93]
	v_mfma_f32_16x16x32_bf16 v[86:89], v[138:141], v[202:205], v[86:89]
	v_mfma_f32_16x16x32_bf16 v[82:85], v[142:145], v[202:205], v[82:85]
	v_mfma_f32_16x16x32_bf16 v[78:81], v[130:133], v[206:209], v[78:81]
	v_mfma_f32_16x16x32_bf16 v[74:77], v[134:137], v[206:209], v[74:77]
	v_mfma_f32_16x16x32_bf16 v[70:73], v[138:141], v[206:209], v[70:73]
	v_mfma_f32_16x16x32_bf16 v[66:69], v[142:145], v[206:209], v[66:69]
	s_cmp_lt_u32 s25, s27
	s_cbranch_scc0 .Lg3_O_sb
	s_sub_u32 s28, s28, 64
	s_subb_u32 s29, s29, 0
	s_cmp_gt_i32 s75, 0
	s_cselect_b32 s30, -1, 4
	s_add_i32 s30, s30, s75
	s_lshl_b32 s30, s30, 15
	s_add_i32 s30, s30, s44
	s_cmp_gt_i32 s75, 1
	s_cselect_b32 s26, -2, 3
	s_add_i32 s26, s26, s75
	s_lshl_b32 s26, s26, 15
	s_add_i32 s26, s26, s44
	s_mov_b32 m0, s26
	v_lshl_add_u64 v[202:203], v[164:165], 0, s[28:29]
	global_load_lds_dwordx4 v[202:203], off
	s_mov_b32 m0, s30
	v_lshl_add_u64 v[202:203], v[202:203], 0, 64
	global_load_lds_dwordx4 v[202:203], off
	s_add_u32 m0, s26, 0x2000
	v_lshl_add_u64 v[202:203], v[162:163], 0, s[28:29]
	global_load_lds_dwordx4 v[202:203], off
	s_add_u32 m0, s30, 0x2000
	v_lshl_add_u64 v[202:203], v[202:203], 0, 64
	global_load_lds_dwordx4 v[202:203], off
	s_add_u32 m0, s26, 0x4000
	v_lshl_add_u64 v[202:203], v[160:161], 0, s[28:29]
	global_load_lds_dwordx4 v[202:203], off
	s_add_u32 m0, s30, 0x4000
	v_lshl_add_u64 v[202:203], v[202:203], 0, 64
	global_load_lds_dwordx4 v[202:203], off
	s_add_u32 m0, s26, 0x6000
	v_lshl_add_u64 v[202:203], v[158:159], 0, s[28:29]
	global_load_lds_dwordx4 v[202:203], off
	s_add_u32 m0, s30, 0x6000
	v_lshl_add_u64 v[202:203], v[202:203], 0, 64
	global_load_lds_dwordx4 v[202:203], off
	s_add_u32 s28, s28, 64
	s_addc_u32 s29, s29, 0
.Lg3_O_sb:
	s_waitcnt lgkmcnt(0)
	v_mfma_f32_16x16x32_bf16 v[60:63], v[130:133], v[146:149], v[60:63]
	ds_read_b128 v[202:205], v64 offset:6144
	ds_read_b128 v[206:209], v64 offset:7168
	s_add_i32 s26, s75, 1
	v_mfma_f32_16x16x32_bf16 v[56:59], v[134:137], v[146:149], v[56:59]
	s_cmp_lg_u32 s26, 5
	s_cselect_b32 s75, s26, 0
	v_mfma_f32_16x16x32_bf16 v[52:55], v[138:141], v[146:149], v[52:55]
	s_add_i32 s25, s25, 1
	s_add_u32 s28, s28, 64
	v_mfma_f32_16x16x32_bf16 v[48:51], v[142:145], v[146:149], v[48:51]
	s_addc_u32 s29, s29, 0
	s_lshl_b32 s26, s75, 15
	v_mfma_f32_16x16x32_bf16 v[44:47], v[130:133], v[150:153], v[44:47]
	v_or_b32_e32 v254, s26, v199
	v_mfma_f32_16x16x32_bf16 v[40:43], v[134:137], v[150:153], v[40:43]
	v_add_u32_e32 v254, v254, v197
	v_mfma_f32_16x16x32_bf16 v[36:39], v[138:141], v[150:153], v[36:39]
	v_add_u32_e32 v64, s26, v198
	v_mfma_f32_16x16x32_bf16 v[32:35], v[142:145], v[150:153], v[32:35]
	v_add_u32_e32 v64, v64, v197
	s_cmp_lt_u32 s25, 29
	s_cbranch_scc0 .Lg3_Ot
	s_cmp_lt_u32 s25, 4
	s_cbranch_scc1 .Lg3_O_early
	s_waitcnt vmcnt(9)
	s_branch .Lg3_O_wd

.Lg3_O_wd:
	s_branch .Lg3_E
.Lg3_Et:
	s_cmp_eq_u32 s25, 29
	s_cbranch_scc0 .Lg3_Et0
	s_waitcnt vmcnt(8)
	s_branch .Lg3_Ew

.Lg4_E:
	s_waitcnt lgkmcnt(0)
	s_barrier
	ds_read_b128 v[246:249], v254 offset:16384
	ds_read_b128 v[250:253], v254 offset:17408
	ds_read_b128 v[150:153], v64
	ds_read_b128 v[146:149], v64 offset:1024
	v_mfma_f32_16x16x32_bf16 v[24:27], v[130:133], v[202:205], v[24:27]
	v_mfma_f32_16x16x32_bf16 v[20:23], v[134:137], v[202:205], v[20:23]
	v_mfma_f32_16x16x32_bf16 v[16:19], v[138:141], v[202:205], v[16:19]
	v_mfma_f32_16x16x32_bf16 v[12:15], v[142:145], v[202:205], v[12:15]
	v_mfma_f32_16x16x32_bf16 v[8:11], v[130:133], v[206:209], v[8:11]
	v_mfma_f32_16x16x32_bf16 v[4:7], v[134:137], v[206:209], v[4:7]
	v_mfma_f32_16x16x32_bf16 v[0:3], v[138:141], v[206:209], v[0:3]
	v_mfma_f32_16x16x32_bf16 v[28:31], v[142:145], v[206:209], v[28:31]
	ds_read_b128 v[138:141], v254 offset:18432
	ds_read_b128 v[142:145], v254 offset:19456
	ds_read_b128 v[202:205], v64 offset:2048
	ds_read_b128 v[206:209], v64 offset:3072
	s_waitcnt lgkmcnt(4)
	v_mfma_f32_16x16x32_bf16 v[126:129], v[246:249], v[150:153], v[126:129]
	v_mfma_f32_16x16x32_bf16 v[122:125], v[250:253], v[150:153], v[122:125]
	v_mfma_f32_16x16x32_bf16 v[110:113], v[246:249], v[146:149], v[110:113]
	v_mfma_f32_16x16x32_bf16 v[106:109], v[250:253], v[146:149], v[106:109]
	s_waitcnt lgkmcnt(2)
	v_mfma_f32_16x16x32_bf16 v[118:121], v[138:141], v[150:153], v[118:121]
	v_mfma_f32_16x16x32_bf16 v[114:117], v[142:145], v[150:153], v[114:117]
	v_mfma_f32_16x16x32_bf16 v[102:105], v[138:141], v[146:149], v[102:105]
	v_mfma_f32_16x16x32_bf16 v[98:101], v[142:145], v[146:149], v[98:101]
	s_waitcnt lgkmcnt(0)
	v_mfma_f32_16x16x32_bf16 v[94:97], v[246:249], v[202:205], v[94:97]
	ds_read_b128 v[146:149], v64 offset:4096
	ds_read_b128 v[150:153], v64 offset:5120
	v_mfma_f32_16x16x32_bf16 v[90:93], v[250:253], v[202:205], v[90:93]
	v_mfma_f32_16x16x32_bf16 v[86:89], v[138:141], v[202:205], v[86:89]
	v_mfma_f32_16x16x32_bf16 v[82:85], v[142:145], v[202:205], v[82:85]
	v_mfma_f32_16x16x32_bf16 v[78:81], v[246:249], v[206:209], v[78:81]
	v_mfma_f32_16x16x32_bf16 v[74:77], v[250:253], v[206:209], v[74:77]
	v_mfma_f32_16x16x32_bf16 v[70:73], v[138:141], v[206:209], v[70:73]
	v_mfma_f32_16x16x32_bf16 v[66:69], v[142:145], v[206:209], v[66:69]
	s_waitcnt lgkmcnt(0)
	v_mfma_f32_16x16x32_bf16 v[60:63], v[246:249], v[146:149], v[60:63]
	ds_read_b128 v[202:205], v64 offset:6144
	ds_read_b128 v[206:209], v64 offset:7168
	s_add_i32 s26, s1, 1
	v_mfma_f32_16x16x32_bf16 v[56:59], v[250:253], v[146:149], v[56:59]
	s_cmp_lg_u32 s26, 5
	s_cselect_b32 s1, s26, 0
	v_mfma_f32_16x16x32_bf16 v[52:55], v[138:141], v[146:149], v[52:55]
	s_add_i32 s75, s75, 1
	s_add_u32 s28, s28, 64
	v_mfma_f32_16x16x32_bf16 v[48:51], v[142:145], v[146:149], v[48:51]
	s_addc_u32 s29, s29, 0
	s_lshl_b32 s26, s1, 15
	v_mfma_f32_16x16x32_bf16 v[44:47], v[246:249], v[150:153], v[44:47]
	v_or_b32_e32 v254, s26, v200
	v_mfma_f32_16x16x32_bf16 v[40:43], v[250:253], v[150:153], v[40:43]
	v_add_u32_e32 v254, v254, v197
	v_mfma_f32_16x16x32_bf16 v[36:39], v[138:141], v[150:153], v[36:39]
	v_add_u32_e32 v64, s26, v199
	v_mfma_f32_16x16x32_bf16 v[32:35], v[142:145], v[150:153], v[32:35]
	v_add_u32_e32 v64, v64, v197
	s_cmp_lt_u32 s75, 29
	s_cbranch_scc0 .Lg4_Et
	s_waitcnt vmcnt(8)
.Lg4_Ew:
.Lg4_O:
	s_waitcnt lgkmcnt(0)
	s_barrier
	ds_read_b128 v[130:133], v254 offset:16384
	ds_read_b128 v[134:137], v254 offset:17408
	ds_read_b128 v[150:153], v64
	ds_read_b128 v[146:149], v64 offset:1024
	v_mfma_f32_16x16x32_bf16 v[24:27], v[246:249], v[202:205], v[24:27]
	v_mfma_f32_16x16x32_bf16 v[20:23], v[250:253], v[202:205], v[20:23]
	v_mfma_f32_16x16x32_bf16 v[16:19], v[138:141], v[202:205], v[16:19]
	v_mfma_f32_16x16x32_bf16 v[12:15], v[142:145], v[202:205], v[12:15]
	v_mfma_f32_16x16x32_bf16 v[8:11], v[246:249], v[206:209], v[8:11]
	v_mfma_f32_16x16x32_bf16 v[4:7], v[250:253], v[206:209], v[4:7]
	v_mfma_f32_16x16x32_bf16 v[0:3], v[138:141], v[206:209], v[0:3]
	v_mfma_f32_16x16x32_bf16 v[28:31], v[142:145], v[206:209], v[28:31]
	ds_read_b128 v[138:141], v254 offset:18432
	ds_read_b128 v[142:145], v254 offset:19456
	s_cmp_lt_u32 s75, s41
	s_cbranch_scc0 .Lg4_O_sa
	s_sub_u32 s28, s28, 64
	s_subb_u32 s29, s29, 0
	s_cmp_gt_i32 s1, 0
	s_cselect_b32 s30, -1, 4
	s_add_i32 s30, s30, s1
	s_lshl_b32 s30, s30, 15
	s_add_i32 s30, s30, s40
	s_cmp_gt_i32 s1, 1
	s_cselect_b32 s26, -2, 3
	s_add_i32 s26, s26, s1
	s_lshl_b32 s26, s26, 15
	s_add_i32 s26, s26, s40
	s_mov_b32 m0, s26
	v_lshl_add_u64 v[202:203], v[164:165], 0, s[28:29]
	global_load_lds_dwordx4 v[202:203], off
	s_mov_b32 m0, s30
	v_lshl_add_u64 v[202:203], v[202:203], 0, 64
	global_load_lds_dwordx4 v[202:203], off
	s_add_u32 m0, s26, 0x2000
	v_lshl_add_u64 v[202:203], v[162:163], 0, s[28:29]
	global_load_lds_dwordx4 v[202:203], off
	s_add_u32 m0, s30, 0x2000
	v_lshl_add_u64 v[202:203], v[202:203], 0, 64
	global_load_lds_dwordx4 v[202:203], off
	s_add_u32 m0, s26, 0x4000
	v_lshl_add_u64 v[202:203], v[160:161], 0, s[28:29]
	global_load_lds_dwordx4 v[202:203], off
	s_add_u32 m0, s30, 0x4000
	v_lshl_add_u64 v[202:203], v[202:203], 0, 64
	global_load_lds_dwordx4 v[202:203], off
	s_add_u32 m0, s26, 0x6000
	v_lshl_add_u64 v[202:203], v[158:159], 0, s[28:29]
	global_load_lds_dwordx4 v[202:203], off
	s_add_u32 m0, s30, 0x6000
	v_lshl_add_u64 v[202:203], v[202:203], 0, 64
	global_load_lds_dwordx4 v[202:203], off
	s_add_u32 s28, s28, 64
	s_addc_u32 s29, s29, 0
.Lg4_O_sa:
	ds_read_b128 v[202:205], v64 offset:2048
	ds_read_b128 v[206:209], v64 offset:3072
	s_waitcnt lgkmcnt(4)
	v_mfma_f32_16x16x32_bf16 v[126:129], v[130:133], v[150:153], v[126:129]
	v_mfma_f32_16x16x32_bf16 v[122:125], v[134:137], v[150:153], v[122:125]
	v_mfma_f32_16x16x32_bf16 v[110:113], v[130:133], v[146:149], v[110:113]
	v_mfma_f32_16x16x32_bf16 v[106:109], v[134:137], v[146:149], v[106:109]
	s_waitcnt lgkmcnt(2)
	v_mfma_f32_16x16x32_bf16 v[118:121], v[138:141], v[150:153], v[118:121]
	v_mfma_f32_16x16x32_bf16 v[114:117], v[142:145], v[150:153], v[114:117]
	v_mfma_f32_16x16x32_bf16 v[102:105], v[138:141], v[146:149], v[102:105]
	v_mfma_f32_16x16x32_bf16 v[98:101], v[142:145], v[146:149], v[98:101]
	s_waitcnt lgkmcnt(0)
	v_mfma_f32_16x16x32_bf16 v[94:97], v[130:133], v[202:205], v[94:97]
	ds_read_b128 v[146:149], v64 offset:4096
	ds_read_b128 v[150:153], v64 offset:5120
	v_mfma_f32_16x16x32_bf16 v[90:93], v[134:137], v[202:205], v[90:93]
	v_mfma_f32_16x16x32_bf16 v[86:89], v[138:141], v[202:205], v[86:89]
	v_mfma_f32_16x16x32_bf16 v[82:85], v[142:145], v[202:205], v[82:85]
	v_mfma_f32_16x16x32_bf16 v[78:81], v[130:133], v[206:209], v[78:81]
	v_mfma_f32_16x16x32_bf16 v[74:77], v[134:137], v[206:209], v[74:77]
	v_mfma_f32_16x16x32_bf16 v[70:73], v[138:141], v[206:209], v[70:73]
	v_mfma_f32_16x16x32_bf16 v[66:69], v[142:145], v[206:209], v[66:69]
	s_cmp_lt_u32 s75, s27
	s_cbranch_scc0 .Lg4_O_sb
	s_sub_u32 s28, s28, 64
	s_subb_u32 s29, s29, 0
	s_cmp_gt_i32 s1, 0
	s_cselect_b32 s30, -1, 4
	s_add_i32 s30, s30, s1
	s_lshl_b32 s30, s30, 15
	s_add_i32 s30, s30, s40
	s_cmp_gt_i32 s1, 1
	s_cselect_b32 s26, -2, 3
	s_add_i32 s26, s26, s1
	s_lshl_b32 s26, s26, 15
	s_add_i32 s26, s26, s40
	s_mov_b32 m0, s26
	v_lshl_add_u64 v[202:203], v[164:165], 0, s[28:29]
	global_load_lds_dwordx4 v[202:203], off
	s_mov_b32 m0, s30
	v_lshl_add_u64 v[202:203], v[202:203], 0, 64
	global_load_lds_dwordx4 v[202:203], off
	s_add_u32 m0, s26, 0x2000
	v_lshl_add_u64 v[202:203], v[162:163], 0, s[28:29]
	global_load_lds_dwordx4 v[202:203], off
	s_add_u32 m0, s30, 0x2000
	v_lshl_add_u64 v[202:203], v[202:203], 0, 64
	global_load_lds_dwordx4 v[202:203], off
	s_add_u32 m0, s26, 0x4000
	v_lshl_add_u64 v[202:203], v[160:161], 0, s[28:29]
	global_load_lds_dwordx4 v[202:203], off
	s_add_u32 m0, s30, 0x4000
	v_lshl_add_u64 v[202:203], v[202:203], 0, 64
	global_load_lds_dwordx4 v[202:203], off
	s_add_u32 m0, s26, 0x6000
	v_lshl_add_u64 v[202:203], v[158:159], 0, s[28:29]
	global_load_lds_dwordx4 v[202:203], off
	s_add_u32 m0, s30, 0x6000
	v_lshl_add_u64 v[202:203], v[202:203], 0, 64
	global_load_lds_dwordx4 v[202:203], off
	s_add_u32 s28, s28, 64
	s_addc_u32 s29, s29, 0
.Lg4_O_sb:
	s_waitcnt lgkmcnt(0)
	v_mfma_f32_16x16x32_bf16 v[60:63], v[130:133], v[146:149], v[60:63]
	ds_read_b128 v[202:205], v64 offset:6144
	ds_read_b128 v[206:209], v64 offset:7168
	s_add_i32 s26, s1, 1
	v_mfma_f32_16x16x32_bf16 v[56:59], v[134:137], v[146:149], v[56:59]
	s_cmp_lg_u32 s26, 5
	s_cselect_b32 s1, s26, 0
	v_mfma_f32_16x16x32_bf16 v[52:55], v[138:141], v[146:149], v[52:55]
	s_add_i32 s75, s75, 1
	s_add_u32 s28, s28, 64
	v_mfma_f32_16x16x32_bf16 v[48:51], v[142:145], v[146:149], v[48:51]
	s_addc_u32 s29, s29, 0
	s_lshl_b32 s26, s1, 15
	v_mfma_f32_16x16x32_bf16 v[44:47], v[130:133], v[150:153], v[44:47]
	v_or_b32_e32 v254, s26, v200
	v_mfma_f32_16x16x32_bf16 v[40:43], v[134:137], v[150:153], v[40:43]
	v_add_u32_e32 v254, v254, v197
	v_mfma_f32_16x16x32_bf16 v[36:39], v[138:141], v[150:153], v[36:39]
	v_add_u32_e32 v64, s26, v199
	v_mfma_f32_16x16x32_bf16 v[32:35], v[142:145], v[150:153], v[32:35]
	v_add_u32_e32 v64, v64, v197
	s_cmp_lt_u32 s75, 29
	s_cbranch_scc0 .Lg4_Ot
	s_cmp_lt_u32 s75, 4
	s_cbranch_scc1 .Lg4_O_early
	s_waitcnt vmcnt(9)
	s_branch .Lg4_O_wd

.Lg4_O_wd:
	s_branch .Lg4_E
.Lg4_Et:
	s_cmp_eq_u32 s75, 29
	s_cbranch_scc0 .Lg4_Et0
	s_waitcnt vmcnt(8)
	s_branch .Lg4_Ew

.Lg4_Ot:
	s_cmp_eq_u32 s75, 32
	s_cbranch_scc1 .Lg4_X
	s_waitcnt vmcnt(1)
	s_branch .Lg4_E

.Lg5_E:
	s_waitcnt lgkmcnt(0)
	s_barrier
	ds_read_b128 v[246:249], v254 offset:16384
	ds_read_b128 v[250:253], v254 offset:17408
	ds_read_b128 v[150:153], v64
	ds_read_b128 v[146:149], v64 offset:1024
	v_mfma_f32_16x16x32_bf16 v[28:31], v[130:133], v[202:205], v[28:31]
	v_mfma_f32_16x16x32_bf16 v[24:27], v[134:137], v[202:205], v[24:27]
	v_mfma_f32_16x16x32_bf16 v[20:23], v[138:141], v[202:205], v[20:23]
	v_mfma_f32_16x16x32_bf16 v[16:19], v[142:145], v[202:205], v[16:19]
	v_mfma_f32_16x16x32_bf16 v[12:15], v[130:133], v[206:209], v[12:15]
	v_mfma_f32_16x16x32_bf16 v[8:11], v[134:137], v[206:209], v[8:11]
	v_mfma_f32_16x16x32_bf16 v[4:7], v[138:141], v[206:209], v[4:7]
	v_mfma_f32_16x16x32_bf16 v[0:3], v[142:145], v[206:209], v[0:3]
	ds_read_b128 v[138:141], v254 offset:18432
	ds_read_b128 v[142:145], v254 offset:19456
	ds_read_b128 v[202:205], v64 offset:2048
	ds_read_b128 v[206:209], v64 offset:3072
	s_waitcnt lgkmcnt(4)
	v_mfma_f32_16x16x32_bf16 v[126:129], v[246:249], v[150:153], v[126:129]
	v_mfma_f32_16x16x32_bf16 v[122:125], v[250:253], v[150:153], v[122:125]
	v_mfma_f32_16x16x32_bf16 v[110:113], v[246:249], v[146:149], v[110:113]
	v_mfma_f32_16x16x32_bf16 v[106:109], v[250:253], v[146:149], v[106:109]
	s_waitcnt lgkmcnt(2)
	v_mfma_f32_16x16x32_bf16 v[118:121], v[138:141], v[150:153], v[118:121]
	v_mfma_f32_16x16x32_bf16 v[114:117], v[142:145], v[150:153], v[114:117]
	v_mfma_f32_16x16x32_bf16 v[102:105], v[138:141], v[146:149], v[102:105]
	v_mfma_f32_16x16x32_bf16 v[98:101], v[142:145], v[146:149], v[98:101]
	s_waitcnt lgkmcnt(0)
	v_mfma_f32_16x16x32_bf16 v[94:97], v[246:249], v[202:205], v[94:97]
	ds_read_b128 v[146:149], v64 offset:4096
	ds_read_b128 v[150:153], v64 offset:5120
	v_mfma_f32_16x16x32_bf16 v[90:93], v[250:253], v[202:205], v[90:93]
	v_mfma_f32_16x16x32_bf16 v[86:89], v[138:141], v[202:205], v[86:89]
	v_mfma_f32_16x16x32_bf16 v[82:85], v[142:145], v[202:205], v[82:85]
	v_mfma_f32_16x16x32_bf16 v[78:81], v[246:249], v[206:209], v[78:81]
	v_mfma_f32_16x16x32_bf16 v[74:77], v[250:253], v[206:209], v[74:77]
	v_mfma_f32_16x16x32_bf16 v[70:73], v[138:141], v[206:209], v[70:73]
	v_mfma_f32_16x16x32_bf16 v[66:69], v[142:145], v[206:209], v[66:69]
	s_waitcnt lgkmcnt(0)
	v_mfma_f32_16x16x32_bf16 v[60:63], v[246:249], v[146:149], v[60:63]
	ds_read_b128 v[202:205], v64 offset:6144
	ds_read_b128 v[206:209], v64 offset:7168
	s_add_i32 s24, s65, 1
	v_mfma_f32_16x16x32_bf16 v[56:59], v[250:253], v[146:149], v[56:59]
	s_cmp_lg_u32 s24, 5
	s_cselect_b32 s65, s24, 0
	v_mfma_f32_16x16x32_bf16 v[52:55], v[138:141], v[146:149], v[52:55]
	s_add_i32 s41, s41, 1
	s_add_u32 s0, s0, 64
	v_mfma_f32_16x16x32_bf16 v[48:51], v[142:145], v[146:149], v[48:51]
	s_addc_u32 s1, s1, 0
	s_lshl_b32 s24, s65, 15
	v_mfma_f32_16x16x32_bf16 v[44:47], v[246:249], v[150:153], v[44:47]
	v_or_b32_e32 v254, s24, v199
	v_mfma_f32_16x16x32_bf16 v[40:43], v[250:253], v[150:153], v[40:43]
	v_add_u32_e32 v254, v254, v197
	v_mfma_f32_16x16x32_bf16 v[36:39], v[138:141], v[150:153], v[36:39]
	v_add_u32_e32 v64, s24, v198
	v_mfma_f32_16x16x32_bf16 v[32:35], v[142:145], v[150:153], v[32:35]
	v_add_u32_e32 v64, v64, v197
	s_cmp_lt_u32 s41, 29
	s_cbranch_scc0 .Lg5_Et
	s_waitcnt vmcnt(8)
.Lg5_Ew:
.Lg5_O:
	s_waitcnt lgkmcnt(0)
	s_barrier
	ds_read_b128 v[130:133], v254 offset:16384
	ds_read_b128 v[134:137], v254 offset:17408
	ds_read_b128 v[150:153], v64
	ds_read_b128 v[146:149], v64 offset:1024
	v_mfma_f32_16x16x32_bf16 v[28:31], v[246:249], v[202:205], v[28:31]
	v_mfma_f32_16x16x32_bf16 v[24:27], v[250:253], v[202:205], v[24:27]
	v_mfma_f32_16x16x32_bf16 v[20:23], v[138:141], v[202:205], v[20:23]
	v_mfma_f32_16x16x32_bf16 v[16:19], v[142:145], v[202:205], v[16:19]
	v_mfma_f32_16x16x32_bf16 v[12:15], v[246:249], v[206:209], v[12:15]
	v_mfma_f32_16x16x32_bf16 v[8:11], v[250:253], v[206:209], v[8:11]
	v_mfma_f32_16x16x32_bf16 v[4:7], v[138:141], v[206:209], v[4:7]
	v_mfma_f32_16x16x32_bf16 v[0:3], v[142:145], v[206:209], v[0:3]
	ds_read_b128 v[138:141], v254 offset:18432
	ds_read_b128 v[142:145], v254 offset:19456
	s_cmp_lt_u32 s41, s29
	s_cbranch_scc0 .Lg5_O_sa
	s_sub_u32 s0, s0, 64
	s_subb_u32 s1, s1, 0
	s_cmp_gt_i32 s65, 0
	s_cselect_b32 s26, -1, 4
	s_add_i32 s26, s26, s65
	s_lshl_b32 s26, s26, 15
	s_add_i32 s26, s26, s28
	s_cmp_gt_i32 s65, 1
	s_cselect_b32 s24, -2, 3
	s_add_i32 s24, s24, s65
	s_lshl_b32 s24, s24, 15
	s_add_i32 s24, s24, s28
	s_mov_b32 m0, s24
	v_lshl_add_u64 v[202:203], v[164:165], 0, s[0:1]
	global_load_lds_dwordx4 v[202:203], off
	s_mov_b32 m0, s26
	v_lshl_add_u64 v[202:203], v[202:203], 0, 64
	global_load_lds_dwordx4 v[202:203], off
	s_add_u32 m0, s24, 0x2000
	v_lshl_add_u64 v[202:203], v[162:163], 0, s[0:1]
	global_load_lds_dwordx4 v[202:203], off
	s_add_u32 m0, s26, 0x2000
	v_lshl_add_u64 v[202:203], v[202:203], 0, 64
	global_load_lds_dwordx4 v[202:203], off
	s_add_u32 m0, s24, 0x4000
	v_lshl_add_u64 v[202:203], v[160:161], 0, s[0:1]
	global_load_lds_dwordx4 v[202:203], off
	s_add_u32 m0, s26, 0x4000
	v_lshl_add_u64 v[202:203], v[202:203], 0, 64
	global_load_lds_dwordx4 v[202:203], off
	s_add_u32 m0, s24, 0x6000
	v_lshl_add_u64 v[202:203], v[158:159], 0, s[0:1]
	global_load_lds_dwordx4 v[202:203], off
	s_add_u32 m0, s26, 0x6000
	v_lshl_add_u64 v[202:203], v[202:203], 0, 64
	global_load_lds_dwordx4 v[202:203], off
	s_add_u32 s0, s0, 64
	s_addc_u32 s1, s1, 0
.Lg5_O_sa:
	ds_read_b128 v[202:205], v64 offset:2048
	ds_read_b128 v[206:209], v64 offset:3072
	s_waitcnt lgkmcnt(4)
	v_mfma_f32_16x16x32_bf16 v[126:129], v[130:133], v[150:153], v[126:129]
	v_mfma_f32_16x16x32_bf16 v[122:125], v[134:137], v[150:153], v[122:125]
	v_mfma_f32_16x16x32_bf16 v[110:113], v[130:133], v[146:149], v[110:113]
	v_mfma_f32_16x16x32_bf16 v[106:109], v[134:137], v[146:149], v[106:109]
	s_waitcnt lgkmcnt(2)
	v_mfma_f32_16x16x32_bf16 v[118:121], v[138:141], v[150:153], v[118:121]
	v_mfma_f32_16x16x32_bf16 v[114:117], v[142:145], v[150:153], v[114:117]
	v_mfma_f32_16x16x32_bf16 v[102:105], v[138:141], v[146:149], v[102:105]
	v_mfma_f32_16x16x32_bf16 v[98:101], v[142:145], v[146:149], v[98:101]
	s_waitcnt lgkmcnt(0)
	v_mfma_f32_16x16x32_bf16 v[94:97], v[130:133], v[202:205], v[94:97]
	ds_read_b128 v[146:149], v64 offset:4096
	ds_read_b128 v[150:153], v64 offset:5120
	v_mfma_f32_16x16x32_bf16 v[90:93], v[134:137], v[202:205], v[90:93]
	v_mfma_f32_16x16x32_bf16 v[86:89], v[138:141], v[202:205], v[86:89]
	v_mfma_f32_16x16x32_bf16 v[82:85], v[142:145], v[202:205], v[82:85]
	v_mfma_f32_16x16x32_bf16 v[78:81], v[130:133], v[206:209], v[78:81]
	v_mfma_f32_16x16x32_bf16 v[74:77], v[134:137], v[206:209], v[74:77]
	v_mfma_f32_16x16x32_bf16 v[70:73], v[138:141], v[206:209], v[70:73]
	v_mfma_f32_16x16x32_bf16 v[66:69], v[142:145], v[206:209], v[66:69]
	s_cmp_lt_u32 s41, s25
	s_cbranch_scc0 .Lg5_O_sb
	s_sub_u32 s0, s0, 64
	s_subb_u32 s1, s1, 0
	s_cmp_gt_i32 s65, 0
	s_cselect_b32 s26, -1, 4
	s_add_i32 s26, s26, s65
	s_lshl_b32 s26, s26, 15
	s_add_i32 s26, s26, s28
	s_cmp_gt_i32 s65, 1
	s_cselect_b32 s24, -2, 3
	s_add_i32 s24, s24, s65
	s_lshl_b32 s24, s24, 15
	s_add_i32 s24, s24, s28
	s_mov_b32 m0, s24
	v_lshl_add_u64 v[202:203], v[164:165], 0, s[0:1]
	global_load_lds_dwordx4 v[202:203], off
	s_mov_b32 m0, s26
	v_lshl_add_u64 v[202:203], v[202:203], 0, 64
	global_load_lds_dwordx4 v[202:203], off
	s_add_u32 m0, s24, 0x2000
	v_lshl_add_u64 v[202:203], v[162:163], 0, s[0:1]
	global_load_lds_dwordx4 v[202:203], off
	s_add_u32 m0, s26, 0x2000
	v_lshl_add_u64 v[202:203], v[202:203], 0, 64
	global_load_lds_dwordx4 v[202:203], off
	s_add_u32 m0, s24, 0x4000
	v_lshl_add_u64 v[202:203], v[160:161], 0, s[0:1]
	global_load_lds_dwordx4 v[202:203], off
	s_add_u32 m0, s26, 0x4000
	v_lshl_add_u64 v[202:203], v[202:203], 0, 64
	global_load_lds_dwordx4 v[202:203], off
	s_add_u32 m0, s24, 0x6000
	v_lshl_add_u64 v[202:203], v[158:159], 0, s[0:1]
	global_load_lds_dwordx4 v[202:203], off
	s_add_u32 m0, s26, 0x6000
	v_lshl_add_u64 v[202:203], v[202:203], 0, 64
	global_load_lds_dwordx4 v[202:203], off
	s_add_u32 s0, s0, 64
	s_addc_u32 s1, s1, 0
.Lg5_O_sb:
	s_waitcnt lgkmcnt(0)
	v_mfma_f32_16x16x32_bf16 v[60:63], v[130:133], v[146:149], v[60:63]
	ds_read_b128 v[202:205], v64 offset:6144
	ds_read_b128 v[206:209], v64 offset:7168
	s_add_i32 s24, s65, 1
	v_mfma_f32_16x16x32_bf16 v[56:59], v[134:137], v[146:149], v[56:59]
	s_cmp_lg_u32 s24, 5
	s_cselect_b32 s65, s24, 0
	v_mfma_f32_16x16x32_bf16 v[52:55], v[138:141], v[146:149], v[52:55]
	s_add_i32 s41, s41, 1
	s_add_u32 s0, s0, 64
	v_mfma_f32_16x16x32_bf16 v[48:51], v[142:145], v[146:149], v[48:51]
	s_addc_u32 s1, s1, 0
	s_lshl_b32 s24, s65, 15
	v_mfma_f32_16x16x32_bf16 v[44:47], v[130:133], v[150:153], v[44:47]
	v_or_b32_e32 v254, s24, v199
	v_mfma_f32_16x16x32_bf16 v[40:43], v[134:137], v[150:153], v[40:43]
	v_add_u32_e32 v254, v254, v197
	v_mfma_f32_16x16x32_bf16 v[36:39], v[138:141], v[150:153], v[36:39]
	v_add_u32_e32 v64, s24, v198
	v_mfma_f32_16x16x32_bf16 v[32:35], v[142:145], v[150:153], v[32:35]
	v_add_u32_e32 v64, v64, v197
	s_cmp_lt_u32 s41, 29
	s_cbranch_scc0 .Lg5_Ot
	s_cmp_lt_u32 s41, 4
	s_cbranch_scc1 .Lg5_O_early
	s_waitcnt vmcnt(9)
	s_branch .Lg5_O_wd

.Lg5_O_wd:
	s_branch .Lg5_E
.Lg5_Et:
	s_cmp_eq_u32 s41, 29
	s_cbranch_scc0 .Lg5_Et0
	s_waitcnt vmcnt(8)
	s_branch .Lg5_Ew

.Lg5_Ot:
	s_cmp_eq_u32 s41, 32
	s_cbranch_scc1 .Lg5_X
	s_waitcnt vmcnt(1)
	s_branch .Lg5_E

.Lg6_E:
	s_waitcnt lgkmcnt(0)
	s_barrier
	ds_read_b128 v[246:249], v254 offset:16384
	ds_read_b128 v[250:253], v254 offset:17408
	ds_read_b128 v[150:153], v64
	ds_read_b128 v[146:149], v64 offset:1024
	v_mfma_f32_16x16x32_bf16 v[28:31], v[130:133], v[202:205], v[28:31]
	v_mfma_f32_16x16x32_bf16 v[24:27], v[134:137], v[202:205], v[24:27]
	v_mfma_f32_16x16x32_bf16 v[20:23], v[138:141], v[202:205], v[20:23]
	v_mfma_f32_16x16x32_bf16 v[16:19], v[142:145], v[202:205], v[16:19]
	v_mfma_f32_16x16x32_bf16 v[12:15], v[130:133], v[206:209], v[12:15]
	v_mfma_f32_16x16x32_bf16 v[8:11], v[134:137], v[206:209], v[8:11]
	v_mfma_f32_16x16x32_bf16 v[4:7], v[138:141], v[206:209], v[4:7]
	v_mfma_f32_16x16x32_bf16 v[0:3], v[142:145], v[206:209], v[0:3]
	ds_read_b128 v[138:141], v254 offset:18432
	ds_read_b128 v[142:145], v254 offset:19456
	ds_read_b128 v[202:205], v64 offset:2048
	ds_read_b128 v[206:209], v64 offset:3072
	s_waitcnt lgkmcnt(4)
	v_mfma_f32_16x16x32_bf16 v[126:129], v[246:249], v[150:153], v[126:129]
	v_mfma_f32_16x16x32_bf16 v[122:125], v[250:253], v[150:153], v[122:125]
	v_mfma_f32_16x16x32_bf16 v[110:113], v[246:249], v[146:149], v[110:113]
	v_mfma_f32_16x16x32_bf16 v[106:109], v[250:253], v[146:149], v[106:109]
	s_waitcnt lgkmcnt(2)
	v_mfma_f32_16x16x32_bf16 v[118:121], v[138:141], v[150:153], v[118:121]
	v_mfma_f32_16x16x32_bf16 v[114:117], v[142:145], v[150:153], v[114:117]
	v_mfma_f32_16x16x32_bf16 v[102:105], v[138:141], v[146:149], v[102:105]
	v_mfma_f32_16x16x32_bf16 v[98:101], v[142:145], v[146:149], v[98:101]
	s_waitcnt lgkmcnt(0)
	v_mfma_f32_16x16x32_bf16 v[94:97], v[246:249], v[202:205], v[94:97]
	ds_read_b128 v[146:149], v64 offset:4096
	ds_read_b128 v[150:153], v64 offset:5120
	v_mfma_f32_16x16x32_bf16 v[90:93], v[250:253], v[202:205], v[90:93]
	v_mfma_f32_16x16x32_bf16 v[86:89], v[138:141], v[202:205], v[86:89]
	v_mfma_f32_16x16x32_bf16 v[82:85], v[142:145], v[202:205], v[82:85]
	v_mfma_f32_16x16x32_bf16 v[78:81], v[246:249], v[206:209], v[78:81]
	v_mfma_f32_16x16x32_bf16 v[74:77], v[250:253], v[206:209], v[74:77]
	v_mfma_f32_16x16x32_bf16 v[70:73], v[138:141], v[206:209], v[70:73]
	v_mfma_f32_16x16x32_bf16 v[66:69], v[142:145], v[206:209], v[66:69]
	s_waitcnt lgkmcnt(0)
	v_mfma_f32_16x16x32_bf16 v[60:63], v[246:249], v[146:149], v[60:63]
	ds_read_b128 v[202:205], v64 offset:6144
	ds_read_b128 v[206:209], v64 offset:7168
	s_add_i32 s25, s65, 1
	v_mfma_f32_16x16x32_bf16 v[56:59], v[250:253], v[146:149], v[56:59]
	s_cmp_lg_u32 s25, 5
	s_cselect_b32 s65, s25, 0
	v_mfma_f32_16x16x32_bf16 v[52:55], v[138:141], v[146:149], v[52:55]
	s_add_i32 s1, s1, 1
	s_add_u32 s28, s28, 64
	v_mfma_f32_16x16x32_bf16 v[48:51], v[142:145], v[146:149], v[48:51]
	s_addc_u32 s29, s29, 0
	s_lshl_b32 s25, s65, 15
	v_mfma_f32_16x16x32_bf16 v[44:47], v[246:249], v[150:153], v[44:47]
	v_or_b32_e32 v254, s25, v199
	v_mfma_f32_16x16x32_bf16 v[40:43], v[250:253], v[150:153], v[40:43]
	v_add_u32_e32 v254, v254, v197
	v_mfma_f32_16x16x32_bf16 v[36:39], v[138:141], v[150:153], v[36:39]
	v_add_u32_e32 v64, s25, v198
	v_mfma_f32_16x16x32_bf16 v[32:35], v[142:145], v[150:153], v[32:35]
	v_add_u32_e32 v64, v64, v197
	s_cmp_lt_u32 s1, 29
	s_cbranch_scc0 .Lg6_Et
	s_waitcnt vmcnt(8)
.Lg6_Ew:
.Lg6_O:
	s_waitcnt lgkmcnt(0)
	s_barrier
	ds_read_b128 v[130:133], v254 offset:16384
	ds_read_b128 v[134:137], v254 offset:17408
	ds_read_b128 v[150:153], v64
	ds_read_b128 v[146:149], v64 offset:1024
	v_mfma_f32_16x16x32_bf16 v[28:31], v[246:249], v[202:205], v[28:31]
	v_mfma_f32_16x16x32_bf16 v[24:27], v[250:253], v[202:205], v[24:27]
	v_mfma_f32_16x16x32_bf16 v[20:23], v[138:141], v[202:205], v[20:23]
	v_mfma_f32_16x16x32_bf16 v[16:19], v[142:145], v[202:205], v[16:19]
	v_mfma_f32_16x16x32_bf16 v[12:15], v[246:249], v[206:209], v[12:15]
	v_mfma_f32_16x16x32_bf16 v[8:11], v[250:253], v[206:209], v[8:11]
	v_mfma_f32_16x16x32_bf16 v[4:7], v[138:141], v[206:209], v[4:7]
	v_mfma_f32_16x16x32_bf16 v[0:3], v[142:145], v[206:209], v[0:3]
	ds_read_b128 v[138:141], v254 offset:18432
	ds_read_b128 v[142:145], v254 offset:19456
	s_cmp_lt_u32 s1, s41
	s_cbranch_scc0 .Lg6_O_sa
	s_sub_u32 s28, s28, 64
	s_subb_u32 s29, s29, 0
	s_cmp_gt_i32 s65, 0
	s_cselect_b32 s27, -1, 4
	s_add_i32 s27, s27, s65
	s_lshl_b32 s27, s27, 15
	s_add_i32 s27, s27, s40
	s_cmp_gt_i32 s65, 1
	s_cselect_b32 s25, -2, 3
	s_add_i32 s25, s25, s65
	s_lshl_b32 s25, s25, 15
	s_add_i32 s25, s25, s40
	s_mov_b32 m0, s25
	v_lshl_add_u64 v[202:203], v[164:165], 0, s[28:29]
	global_load_lds_dwordx4 v[202:203], off
	s_mov_b32 m0, s27
	v_lshl_add_u64 v[202:203], v[202:203], 0, 64
	global_load_lds_dwordx4 v[202:203], off
	s_add_u32 m0, s25, 0x2000
	v_lshl_add_u64 v[202:203], v[162:163], 0, s[28:29]
	global_load_lds_dwordx4 v[202:203], off
	s_add_u32 m0, s27, 0x2000
	v_lshl_add_u64 v[202:203], v[202:203], 0, 64
	global_load_lds_dwordx4 v[202:203], off
	s_add_u32 m0, s25, 0x4000
	v_lshl_add_u64 v[202:203], v[160:161], 0, s[28:29]
	global_load_lds_dwordx4 v[202:203], off
	s_add_u32 m0, s27, 0x4000
	v_lshl_add_u64 v[202:203], v[202:203], 0, 64
	global_load_lds_dwordx4 v[202:203], off
	s_add_u32 m0, s25, 0x6000
	v_lshl_add_u64 v[202:203], v[158:159], 0, s[28:29]
	global_load_lds_dwordx4 v[202:203], off
	s_add_u32 m0, s27, 0x6000
	v_lshl_add_u64 v[202:203], v[202:203], 0, 64
	global_load_lds_dwordx4 v[202:203], off
	s_add_u32 s28, s28, 64
	s_addc_u32 s29, s29, 0
.Lg6_O_sa:
	ds_read_b128 v[202:205], v64 offset:2048
	ds_read_b128 v[206:209], v64 offset:3072
	s_waitcnt lgkmcnt(4)
	v_mfma_f32_16x16x32_bf16 v[126:129], v[130:133], v[150:153], v[126:129]
	v_mfma_f32_16x16x32_bf16 v[122:125], v[134:137], v[150:153], v[122:125]
	v_mfma_f32_16x16x32_bf16 v[110:113], v[130:133], v[146:149], v[110:113]
	v_mfma_f32_16x16x32_bf16 v[106:109], v[134:137], v[146:149], v[106:109]
	s_waitcnt lgkmcnt(2)
	v_mfma_f32_16x16x32_bf16 v[118:121], v[138:141], v[150:153], v[118:121]
	v_mfma_f32_16x16x32_bf16 v[114:117], v[142:145], v[150:153], v[114:117]
	v_mfma_f32_16x16x32_bf16 v[102:105], v[138:141], v[146:149], v[102:105]
	v_mfma_f32_16x16x32_bf16 v[98:101], v[142:145], v[146:149], v[98:101]
	s_waitcnt lgkmcnt(0)
	v_mfma_f32_16x16x32_bf16 v[94:97], v[130:133], v[202:205], v[94:97]
	ds_read_b128 v[146:149], v64 offset:4096
	ds_read_b128 v[150:153], v64 offset:5120
	v_mfma_f32_16x16x32_bf16 v[90:93], v[134:137], v[202:205], v[90:93]
	v_mfma_f32_16x16x32_bf16 v[86:89], v[138:141], v[202:205], v[86:89]
	v_mfma_f32_16x16x32_bf16 v[82:85], v[142:145], v[202:205], v[82:85]
	v_mfma_f32_16x16x32_bf16 v[78:81], v[130:133], v[206:209], v[78:81]
	v_mfma_f32_16x16x32_bf16 v[74:77], v[134:137], v[206:209], v[74:77]
	v_mfma_f32_16x16x32_bf16 v[70:73], v[138:141], v[206:209], v[70:73]
	v_mfma_f32_16x16x32_bf16 v[66:69], v[142:145], v[206:209], v[66:69]
	s_cmp_lt_u32 s1, s26
	s_cbranch_scc0 .Lg6_O_sb
	s_sub_u32 s28, s28, 64
	s_subb_u32 s29, s29, 0
	s_cmp_gt_i32 s65, 0
	s_cselect_b32 s27, -1, 4
	s_add_i32 s27, s27, s65
	s_lshl_b32 s27, s27, 15
	s_add_i32 s27, s27, s40
	s_cmp_gt_i32 s65, 1
	s_cselect_b32 s25, -2, 3
	s_add_i32 s25, s25, s65
	s_lshl_b32 s25, s25, 15
	s_add_i32 s25, s25, s40
	s_mov_b32 m0, s25
	v_lshl_add_u64 v[202:203], v[164:165], 0, s[28:29]
	global_load_lds_dwordx4 v[202:203], off
	s_mov_b32 m0, s27
	v_lshl_add_u64 v[202:203], v[202:203], 0, 64
	global_load_lds_dwordx4 v[202:203], off
	s_add_u32 m0, s25, 0x2000
	v_lshl_add_u64 v[202:203], v[162:163], 0, s[28:29]
	global_load_lds_dwordx4 v[202:203], off
	s_add_u32 m0, s27, 0x2000
	v_lshl_add_u64 v[202:203], v[202:203], 0, 64
	global_load_lds_dwordx4 v[202:203], off
	s_add_u32 m0, s25, 0x4000
	v_lshl_add_u64 v[202:203], v[160:161], 0, s[28:29]
	global_load_lds_dwordx4 v[202:203], off
	s_add_u32 m0, s27, 0x4000
	v_lshl_add_u64 v[202:203], v[202:203], 0, 64
	global_load_lds_dwordx4 v[202:203], off
	s_add_u32 m0, s25, 0x6000
	v_lshl_add_u64 v[202:203], v[158:159], 0, s[28:29]
	global_load_lds_dwordx4 v[202:203], off
	s_add_u32 m0, s27, 0x6000
	v_lshl_add_u64 v[202:203], v[202:203], 0, 64
	global_load_lds_dwordx4 v[202:203], off
	s_add_u32 s28, s28, 64
	s_addc_u32 s29, s29, 0
.Lg6_O_sb:
	s_waitcnt lgkmcnt(0)
	v_mfma_f32_16x16x32_bf16 v[60:63], v[130:133], v[146:149], v[60:63]
	ds_read_b128 v[202:205], v64 offset:6144
	ds_read_b128 v[206:209], v64 offset:7168
	s_add_i32 s25, s65, 1
	v_mfma_f32_16x16x32_bf16 v[56:59], v[134:137], v[146:149], v[56:59]
	s_cmp_lg_u32 s25, 5
	s_cselect_b32 s65, s25, 0
	v_mfma_f32_16x16x32_bf16 v[52:55], v[138:141], v[146:149], v[52:55]
	s_add_i32 s1, s1, 1
	s_add_u32 s28, s28, 64
	v_mfma_f32_16x16x32_bf16 v[48:51], v[142:145], v[146:149], v[48:51]
	s_addc_u32 s29, s29, 0
	s_lshl_b32 s25, s65, 15
	v_mfma_f32_16x16x32_bf16 v[44:47], v[130:133], v[150:153], v[44:47]
	v_or_b32_e32 v254, s25, v199
	v_mfma_f32_16x16x32_bf16 v[40:43], v[134:137], v[150:153], v[40:43]
	v_add_u32_e32 v254, v254, v197
	v_mfma_f32_16x16x32_bf16 v[36:39], v[138:141], v[150:153], v[36:39]
	v_add_u32_e32 v64, s25, v198
	v_mfma_f32_16x16x32_bf16 v[32:35], v[142:145], v[150:153], v[32:35]
	v_add_u32_e32 v64, v64, v197
	s_cmp_lt_u32 s1, 29
	s_cbranch_scc0 .Lg6_Ot
	s_cmp_lt_u32 s1, 4
	s_cbranch_scc1 .Lg6_O_early
	s_waitcnt vmcnt(9)
	s_branch .Lg6_O_wd

.Lg6_O_wd:
	s_branch .Lg6_E
.Lg6_Et:
	s_cmp_eq_u32 s1, 29
	s_cbranch_scc0 .Lg6_Et0
	s_waitcnt vmcnt(8)
	s_branch .Lg6_Ew

.Lg6_Ot:
	s_cmp_eq_u32 s1, 32
	s_cbranch_scc1 .Lg6_X
	s_waitcnt vmcnt(1)
	s_branch .Lg6_E

.Lg7_E:
	s_waitcnt lgkmcnt(0)
	s_barrier
	ds_read_b128 v[246:249], v254 offset:16384
	ds_read_b128 v[250:253], v254 offset:17408
	ds_read_b128 v[150:153], v64
	ds_read_b128 v[146:149], v64 offset:1024
	v_mfma_f32_16x16x32_bf16 v[28:31], v[130:133], v[202:205], v[28:31]
	v_mfma_f32_16x16x32_bf16 v[24:27], v[134:137], v[202:205], v[24:27]
	v_mfma_f32_16x16x32_bf16 v[20:23], v[138:141], v[202:205], v[20:23]
	v_mfma_f32_16x16x32_bf16 v[16:19], v[142:145], v[202:205], v[16:19]
	v_mfma_f32_16x16x32_bf16 v[12:15], v[130:133], v[206:209], v[12:15]
	v_mfma_f32_16x16x32_bf16 v[8:11], v[134:137], v[206:209], v[8:11]
	v_mfma_f32_16x16x32_bf16 v[4:7], v[138:141], v[206:209], v[4:7]
	v_mfma_f32_16x16x32_bf16 v[0:3], v[142:145], v[206:209], v[0:3]
	ds_read_b128 v[138:141], v254 offset:18432
	ds_read_b128 v[142:145], v254 offset:19456
	ds_read_b128 v[202:205], v64 offset:2048
	ds_read_b128 v[206:209], v64 offset:3072
	s_waitcnt lgkmcnt(4)
	v_mfma_f32_16x16x32_bf16 v[126:129], v[246:249], v[150:153], v[126:129]
	v_mfma_f32_16x16x32_bf16 v[122:125], v[250:253], v[150:153], v[122:125]
	v_mfma_f32_16x16x32_bf16 v[110:113], v[246:249], v[146:149], v[110:113]
	v_mfma_f32_16x16x32_bf16 v[106:109], v[250:253], v[146:149], v[106:109]
	s_waitcnt lgkmcnt(2)
	v_mfma_f32_16x16x32_bf16 v[118:121], v[138:141], v[150:153], v[118:121]
	v_mfma_f32_16x16x32_bf16 v[114:117], v[142:145], v[150:153], v[114:117]
	v_mfma_f32_16x16x32_bf16 v[102:105], v[138:141], v[146:149], v[102:105]
	v_mfma_f32_16x16x32_bf16 v[98:101], v[142:145], v[146:149], v[98:101]
	s_waitcnt lgkmcnt(0)
	v_mfma_f32_16x16x32_bf16 v[94:97], v[246:249], v[202:205], v[94:97]
	ds_read_b128 v[146:149], v64 offset:4096
	ds_read_b128 v[150:153], v64 offset:5120
	v_mfma_f32_16x16x32_bf16 v[90:93], v[250:253], v[202:205], v[90:93]
	v_mfma_f32_16x16x32_bf16 v[86:89], v[138:141], v[202:205], v[86:89]
	v_mfma_f32_16x16x32_bf16 v[82:85], v[142:145], v[202:205], v[82:85]
	v_mfma_f32_16x16x32_bf16 v[78:81], v[246:249], v[206:209], v[78:81]
	v_mfma_f32_16x16x32_bf16 v[74:77], v[250:253], v[206:209], v[74:77]
	v_mfma_f32_16x16x32_bf16 v[70:73], v[138:141], v[206:209], v[70:73]
	v_mfma_f32_16x16x32_bf16 v[66:69], v[142:145], v[206:209], v[66:69]
	s_waitcnt lgkmcnt(0)
	v_mfma_f32_16x16x32_bf16 v[60:63], v[246:249], v[146:149], v[60:63]
	ds_read_b128 v[202:205], v64 offset:6144
	ds_read_b128 v[206:209], v64 offset:7168
	s_add_i32 s26, s41, 1
	v_mfma_f32_16x16x32_bf16 v[56:59], v[250:253], v[146:149], v[56:59]
	s_cmp_lg_u32 s26, 5
	s_cselect_b32 s41, s26, 0
	v_mfma_f32_16x16x32_bf16 v[52:55], v[138:141], v[146:149], v[52:55]
	s_add_i32 s45, s45, 1
	s_add_u32 s0, s0, 64
	v_mfma_f32_16x16x32_bf16 v[48:51], v[142:145], v[146:149], v[48:51]
	s_addc_u32 s1, s1, 0
	s_lshl_b32 s26, s41, 15
	v_mfma_f32_16x16x32_bf16 v[44:47], v[246:249], v[150:153], v[44:47]
	v_or_b32_e32 v254, s26, v199
	v_mfma_f32_16x16x32_bf16 v[40:43], v[250:253], v[150:153], v[40:43]
	v_add_u32_e32 v254, v254, v197
	v_mfma_f32_16x16x32_bf16 v[36:39], v[138:141], v[150:153], v[36:39]
	v_add_u32_e32 v64, s26, v198
	v_mfma_f32_16x16x32_bf16 v[32:35], v[142:145], v[150:153], v[32:35]
	v_add_u32_e32 v64, v64, v197
	s_cmp_lt_u32 s45, 85
	s_cbranch_scc0 .Lg7_Et
	s_waitcnt vmcnt(8)
.Lg7_Ew:
.Lg7_O:
	s_waitcnt lgkmcnt(0)
	s_barrier
	ds_read_b128 v[130:133], v254 offset:16384
	ds_read_b128 v[134:137], v254 offset:17408
	ds_read_b128 v[150:153], v64
	ds_read_b128 v[146:149], v64 offset:1024
	v_mfma_f32_16x16x32_bf16 v[28:31], v[246:249], v[202:205], v[28:31]
	v_mfma_f32_16x16x32_bf16 v[24:27], v[250:253], v[202:205], v[24:27]
	v_mfma_f32_16x16x32_bf16 v[20:23], v[138:141], v[202:205], v[20:23]
	v_mfma_f32_16x16x32_bf16 v[16:19], v[142:145], v[202:205], v[16:19]
	v_mfma_f32_16x16x32_bf16 v[12:15], v[246:249], v[206:209], v[12:15]
	v_mfma_f32_16x16x32_bf16 v[8:11], v[250:253], v[206:209], v[8:11]
	v_mfma_f32_16x16x32_bf16 v[4:7], v[138:141], v[206:209], v[4:7]
	v_mfma_f32_16x16x32_bf16 v[0:3], v[142:145], v[206:209], v[0:3]
	ds_read_b128 v[138:141], v254 offset:18432
	ds_read_b128 v[142:145], v254 offset:19456
	s_cmp_lt_u32 s45, s31
	s_cbranch_scc0 .Lg7_O_sa
	s_sub_u32 s0, s0, 64
	s_subb_u32 s1, s1, 0
	s_cmp_gt_i32 s41, 0
	s_cselect_b32 s28, -1, 4
	s_add_i32 s28, s28, s41
	s_lshl_b32 s28, s28, 15
	s_add_i32 s28, s28, s30
	s_cmp_gt_i32 s41, 1
	s_cselect_b32 s26, -2, 3
	s_add_i32 s26, s26, s41
	s_lshl_b32 s26, s26, 15
	s_add_i32 s26, s26, s30
	s_mov_b32 m0, s26
	v_lshl_add_u64 v[202:203], v[164:165], 0, s[0:1]
	global_load_lds_dwordx4 v[202:203], off
	s_mov_b32 m0, s28
	v_lshl_add_u64 v[202:203], v[202:203], 0, 64
	global_load_lds_dwordx4 v[202:203], off
	s_add_u32 m0, s26, 0x2000
	v_lshl_add_u64 v[202:203], v[162:163], 0, s[0:1]
	global_load_lds_dwordx4 v[202:203], off
	s_add_u32 m0, s28, 0x2000
	v_lshl_add_u64 v[202:203], v[202:203], 0, 64
	global_load_lds_dwordx4 v[202:203], off
	s_add_u32 m0, s26, 0x4000
	v_lshl_add_u64 v[202:203], v[160:161], 0, s[0:1]
	global_load_lds_dwordx4 v[202:203], off
	s_add_u32 m0, s28, 0x4000
	v_lshl_add_u64 v[202:203], v[202:203], 0, 64
	global_load_lds_dwordx4 v[202:203], off
	s_add_u32 m0, s26, 0x6000
	v_lshl_add_u64 v[202:203], v[158:159], 0, s[0:1]
	global_load_lds_dwordx4 v[202:203], off
	s_add_u32 m0, s28, 0x6000
	v_lshl_add_u64 v[202:203], v[202:203], 0, 64
	global_load_lds_dwordx4 v[202:203], off
	s_add_u32 s0, s0, 64
	s_addc_u32 s1, s1, 0
.Lg7_O_sa:
	ds_read_b128 v[202:205], v64 offset:2048
	ds_read_b128 v[206:209], v64 offset:3072
	s_waitcnt lgkmcnt(4)
	v_mfma_f32_16x16x32_bf16 v[126:129], v[130:133], v[150:153], v[126:129]
	v_mfma_f32_16x16x32_bf16 v[122:125], v[134:137], v[150:153], v[122:125]
	v_mfma_f32_16x16x32_bf16 v[110:113], v[130:133], v[146:149], v[110:113]
	v_mfma_f32_16x16x32_bf16 v[106:109], v[134:137], v[146:149], v[106:109]
	s_waitcnt lgkmcnt(2)
	v_mfma_f32_16x16x32_bf16 v[118:121], v[138:141], v[150:153], v[118:121]
	v_mfma_f32_16x16x32_bf16 v[114:117], v[142:145], v[150:153], v[114:117]
	v_mfma_f32_16x16x32_bf16 v[102:105], v[138:141], v[146:149], v[102:105]
	v_mfma_f32_16x16x32_bf16 v[98:101], v[142:145], v[146:149], v[98:101]
	s_waitcnt lgkmcnt(0)
	v_mfma_f32_16x16x32_bf16 v[94:97], v[130:133], v[202:205], v[94:97]
	ds_read_b128 v[146:149], v64 offset:4096
	ds_read_b128 v[150:153], v64 offset:5120
	v_mfma_f32_16x16x32_bf16 v[90:93], v[134:137], v[202:205], v[90:93]
	v_mfma_f32_16x16x32_bf16 v[86:89], v[138:141], v[202:205], v[86:89]
	v_mfma_f32_16x16x32_bf16 v[82:85], v[142:145], v[202:205], v[82:85]
	v_mfma_f32_16x16x32_bf16 v[78:81], v[130:133], v[206:209], v[78:81]
	v_mfma_f32_16x16x32_bf16 v[74:77], v[134:137], v[206:209], v[74:77]
	v_mfma_f32_16x16x32_bf16 v[70:73], v[138:141], v[206:209], v[70:73]
	v_mfma_f32_16x16x32_bf16 v[66:69], v[142:145], v[206:209], v[66:69]
	s_cmp_lt_u32 s45, s27
	s_cbranch_scc0 .Lg7_O_sb
	s_sub_u32 s0, s0, 64
	s_subb_u32 s1, s1, 0
	s_cmp_gt_i32 s41, 0
	s_cselect_b32 s28, -1, 4
	s_add_i32 s28, s28, s41
	s_lshl_b32 s28, s28, 15
	s_add_i32 s28, s28, s30
	s_cmp_gt_i32 s41, 1
	s_cselect_b32 s26, -2, 3
	s_add_i32 s26, s26, s41
	s_lshl_b32 s26, s26, 15
	s_add_i32 s26, s26, s30
	s_mov_b32 m0, s26
	v_lshl_add_u64 v[202:203], v[164:165], 0, s[0:1]
	global_load_lds_dwordx4 v[202:203], off
	s_mov_b32 m0, s28
	v_lshl_add_u64 v[202:203], v[202:203], 0, 64
	global_load_lds_dwordx4 v[202:203], off
	s_add_u32 m0, s26, 0x2000
	v_lshl_add_u64 v[202:203], v[162:163], 0, s[0:1]
	global_load_lds_dwordx4 v[202:203], off
	s_add_u32 m0, s28, 0x2000
	v_lshl_add_u64 v[202:203], v[202:203], 0, 64
	global_load_lds_dwordx4 v[202:203], off
	s_add_u32 m0, s26, 0x4000
	v_lshl_add_u64 v[202:203], v[160:161], 0, s[0:1]
	global_load_lds_dwordx4 v[202:203], off
	s_add_u32 m0, s28, 0x4000
	v_lshl_add_u64 v[202:203], v[202:203], 0, 64
	global_load_lds_dwordx4 v[202:203], off
	s_add_u32 m0, s26, 0x6000
	v_lshl_add_u64 v[202:203], v[158:159], 0, s[0:1]
	global_load_lds_dwordx4 v[202:203], off
	s_add_u32 m0, s28, 0x6000
	v_lshl_add_u64 v[202:203], v[202:203], 0, 64
	global_load_lds_dwordx4 v[202:203], off
	s_add_u32 s0, s0, 64
	s_addc_u32 s1, s1, 0
.Lg7_O_sb:
	s_waitcnt lgkmcnt(0)
	v_mfma_f32_16x16x32_bf16 v[60:63], v[130:133], v[146:149], v[60:63]
	ds_read_b128 v[202:205], v64 offset:6144
	ds_read_b128 v[206:209], v64 offset:7168
	s_add_i32 s26, s41, 1
	v_mfma_f32_16x16x32_bf16 v[56:59], v[134:137], v[146:149], v[56:59]
	s_cmp_lg_u32 s26, 5
	s_cselect_b32 s41, s26, 0
	v_mfma_f32_16x16x32_bf16 v[52:55], v[138:141], v[146:149], v[52:55]
	s_add_i32 s45, s45, 1
	s_add_u32 s0, s0, 64
	v_mfma_f32_16x16x32_bf16 v[48:51], v[142:145], v[146:149], v[48:51]
	s_addc_u32 s1, s1, 0
	s_lshl_b32 s26, s41, 15
	v_mfma_f32_16x16x32_bf16 v[44:47], v[130:133], v[150:153], v[44:47]
	v_or_b32_e32 v254, s26, v199
	v_mfma_f32_16x16x32_bf16 v[40:43], v[134:137], v[150:153], v[40:43]
	v_add_u32_e32 v254, v254, v197
	v_mfma_f32_16x16x32_bf16 v[36:39], v[138:141], v[150:153], v[36:39]
	v_add_u32_e32 v64, s26, v198
	v_mfma_f32_16x16x32_bf16 v[32:35], v[142:145], v[150:153], v[32:35]
	v_add_u32_e32 v64, v64, v197
	s_cmp_lt_u32 s45, 85
	s_cbranch_scc0 .Lg7_Ot
	s_cmp_lt_u32 s45, 4
	s_cbranch_scc1 .Lg7_O_early
	s_waitcnt vmcnt(9)
	s_branch .Lg7_O_wd

.Lg7_O_wd:
	s_branch .Lg7_E
.Lg7_Et:
	s_cmp_eq_u32 s45, 85
	s_cbranch_scc0 .Lg7_Et0
	s_waitcnt vmcnt(8)
	s_branch .Lg7_Ew

.Lg7_Ot:
	s_cmp_eq_u32 s45, 88
	s_cbranch_scc1 .Lg7_X
	s_waitcnt vmcnt(1)
	s_branch .Lg7_E
